# prologue wait covers third slot for merged k-loops (race fix) + S5 recurrence as in-place fmac chains + gates sqrt without denormal-range scaling
# speedup vs baseline: 1.0181x; 1.0018x over previous
; #define PG8_STAGE(bufoff, gbase, voff) do { _Pragma("unroll") for (int _i = 0; _i < 2; ++_i) \
;         __builtin_amdgcn_global_load_lds((const unsigned*)((const char*)(gbase) + (voff)[_i]), (LAS unsigned*)(lds + (bufoff) + ldsw + _i * 8192), 16, 0, 0); } while (0)
; #define PG8_WAIT_V(n) asm volatile("s_waitcnt vmcnt(" #n ")" ::: "memory")
; #define PG8_BAR __builtin_amdgcn_s_barrier()
; template <class Epi>
; __device__ __forceinline__ void gemm_phase(LAS unsigned char* lds, const Gemm g, const StaticOrder& S, const Epi& E) {
;     ...
;     const int tid = tid_, wid = __builtin_amdgcn_readfirstlane(tid >> 6), lane = tid & 63, wr = wid >> 2, wc = wid & 3, fr = lane & 15, fq = lane >> 4;
;     const int K = g.K, nt = K / BK;
;     unsigned voffA[2], voffB[2];
; #pragma unroll
;     for (int i = 0; i < 2; ++i) { int R, C; stage_rc(tid * 16 + i * 8192, R, C); const int Rb = Epi::PERM ? ((R & ~31) + perm32(R & 31)) : R;
;         const int Ra = Epi::ROWPERM ? ((R & ~63) + 4 * (R & 15) + ((R >> 4) & 3)) : R;
;         voffA[i] = (unsigned)(Ra * g.lda + C) * 2u; voffB[i] = (unsigned)(Rb * g.ldb + C) * 2u; }
;     const size_t kstep = (size_t)(BK * 2);
;     const size_t hstepA = (size_t)HALF * g.lda * 2, hstepB = (size_t)HALF * g.ldb * 2;
;     const size_t tstepA = 2 * hstepA, tstepB = 2 * hstepB;
;     const unsigned ldsw = (unsigned)wid * 1024u;
;     const int aoff = lds_byte(wr * 64 + fr, fq * 8), boff = lds_byte(wc * 32 + fr, fq * 8);
;     ...
;     PG8_STAGE(PG8_SB(0, 0), cB, voffB); PG8_STAGE(PG8_SA(0, 0), cA, voffA); PG8_STAGE(PG8_SB(0, 1), cB + hstepB, voffB); PG8_STAGE(PG8_SA(0, 1), cA + hstepA, voffA);
;     if (wr == 1) PG8_BAR;
;     PG8_WAIT_V(4); PG8_BAR;
;     PG8_STAGE(PG8_SB(1, 0), cB + kstep, voffB); PG8_STAGE(PG8_SA(1, 0), cA + kstep, voffA); PG8_STAGE(PG8_SB(1, 1), cB + hstepB + kstep, voffB);
;     PG8_WAIT_V(6); PG8_BAR;
.LBB0_304:
	s_lshl_b32 s9, s9, 5
	s_mov_b64 s[14:15], 0x80
	s_and_b32 s9, s9, 0x60
	s_add_i32 m0, s45, 0x18000
	v_lshl_add_u64 v[6:7], v[6:7], 0, s[14:15]
	s_lshl_b32 s16, s22, 13
	s_lshl_b32 s17, s9, 7
	s_waitcnt vmcnt(2)
	s_barrier
	global_load_lds_dwordx4 v[6:7], off
	v_lshl_add_u64 v[4:5], v[4:5], 0, s[14:15]
	s_add_i32 m0, s45, 0x1a000
	s_add_i32 s68, s45, 0x8000
	s_add_i32 s69, s45, 0xa000
	global_load_lds_dwordx4 v[4:5], off
	v_lshl_add_u64 v[0:1], v[0:1], 0, s[14:15]
	s_mov_b32 m0, s68
	s_add_u32 s10, s38, 0x40080
	global_load_lds_dwordx4 v[0:1], off
	v_lshl_add_u64 v[0:1], v[2:3], 0, s[14:15]
	s_mov_b32 m0, s69
	s_addc_u32 s11, s39, 0
	global_load_lds_dwordx4 v[0:1], off
	s_add_i32 m0, s45, 0x1c000
	v_lshl_add_u64 v[0:1], s[10:11], 0, v[214:215]
	global_load_lds_dwordx4 v[0:1], off
	v_lshl_add_u64 v[0:1], s[10:11], 0, v[210:211]
	s_add_i32 m0, s45, 0x1e000
	s_sext_i32_i16 s35, s8
	global_load_lds_dwordx4 v[0:1], off
	v_lshrrev_b32_e32 v1, 1, v13
	v_and_b32_e32 v0, 15, v13
	v_and_b32_e32 v1, 24, v1
	v_lshlrev_b32_e32 v2, 1, v1
	v_lshlrev_b32_e32 v3, 2, v0
	v_lshl_or_b32 v2, v0, 6, v2
	v_and_b32_e32 v4, 32, v3
	v_or_b32_e32 v218, s9, v1
	v_cmp_eq_u32_e64 s[8:9], 15, v0
	v_bitop3_b32 v5, v2, s16, v4 bitop3:0xde
	v_bitop3_b32 v235, v2, s17, v4 bitop3:0xde
	s_lshl_b32 s26, s22, 11
	s_and_b64 s[16:17], s[8:9], s[12:13]
	s_cmp_gt_i32 s22, 0
	v_cmp_eq_u32_e32 vcc, 0, v0
	s_cselect_b64 s[12:13], -1, 0
	s_and_b64 s[18:19], vcc, s[12:13]
	s_cmp_gt_i32 s22, -2
	v_or_b32_e32 v0, s22, v0
	s_cselect_b64 s[12:13], -1, 0
	v_cmp_eq_u32_e64 s[10:11], 0, v0
	v_lshl_or_b32 v236, s22, 6, v3
	s_and_b64 s[22:23], vcc, s[12:13]
	v_lshlrev_b32_e32 v0, 2, v218
	v_mov_b32_e32 v1, v215
	s_add_i32 s12, s26, 0
	v_lshl_add_u64 v[220:221], s[56:57], 0, v[0:1]
	v_lshl_add_u64 v[222:223], s[58:59], 0, v[0:1]
	s_add_i32 s13, s12, 0x20000
	s_add_i32 s12, s12, 0x1f800
	v_and_b32_e32 v1, 1, v14
	v_add_u32_e32 v237, s13, v0
	v_add_u32_e32 v238, s12, v0
	v_add3_u32 v0, v16, v17, v18
	v_lshlrev_b32_e32 v1, 6, v1
	v_lshl_or_b32 v0, v0, 11, v1
	s_mov_b64 s[24:25], 0x40080
	v_lshl_add_u32 v0, v15, 1, v0
	v_mov_b32_e32 v1, v215
	v_lshl_add_u64 v[224:225], v[0:1], 0, s[24:25]
	v_and_b32_e32 v1, 1, v8
	v_add3_u32 v0, v10, v11, v12
	v_lshlrev_b32_e32 v1, 6, v1
	s_waitcnt vmcnt(6)
	v_lshl_or_b32 v0, v0, 11, v1
	v_lshl_add_u32 v0, v9, 1, v0
	v_mov_b32_e32 v1, v215
	s_add_i32 s72, 0, 0x10000
	s_add_i32 s73, 0, 0x14000
	s_ashr_i32 s70, s50, 31
	s_mov_b32 s71, s50
	v_add_u32_e32 v239, 0xfffffe10, v237
	v_add_u32_e32 v240, 0xfffffa10, v237
	v_add_u32_e32 v241, 0xfffffc10, v237
	v_add_u32_e32 v242, 0xfffff810, v237
	v_lshl_add_u64 v[226:227], v[0:1], 0, s[24:25]
	v_mov_b64_e32 v[228:229], 0xb00
	v_mov_b64_e32 v[230:231], 0xaff
	v_add_u32_e32 v243, s72, v235
	v_add_u32_e32 v244, 0, v5
	v_add_u32_e32 v245, s73, v235
	s_movk_i32 s74, 0x1600
	s_barrier
	s_branch .LBB0_306

; #define PG8_STAGE(bufoff, gbase, voff) do { _Pragma("unroll") for (int _i = 0; _i < 2; ++_i) \
;         __builtin_amdgcn_global_load_lds((const unsigned*)((const char*)(gbase) + (voff)[_i]), (LAS unsigned*)(lds + (bufoff) + ldsw + _i * 8192), 16, 0, 0); } while (0)
; #define PG8_WAIT_V(n) asm volatile("s_waitcnt vmcnt(" #n ")" ::: "memory")
; #define PG8_BAR __builtin_amdgcn_s_barrier()
; template <class Epi>
; __device__ __forceinline__ void gemm_phase(LAS unsigned char* lds, const Gemm g, const StaticOrder& S, const Epi& E) {
;     ...
;     PG8_STAGE(PG8_SB(0, 0), cB, voffB); PG8_STAGE(PG8_SA(0, 0), cA, voffA); PG8_STAGE(PG8_SB(0, 1), cB + hstepB, voffB); PG8_STAGE(PG8_SA(0, 1), cA + hstepA, voffA);
;     if (wr == 1) PG8_BAR;
;     PG8_WAIT_V(4); PG8_BAR;
;     PG8_STAGE(PG8_SB(1, 0), cB + kstep, voffB); PG8_STAGE(PG8_SA(1, 0), cA + kstep, voffA); PG8_STAGE(PG8_SB(1, 1), cB + hstepB + kstep, voffB);
;     PG8_WAIT_V(6); PG8_BAR;
.LBB0_399:
	s_lshl_b32 s10, s10, 5
	s_mov_b64 s[16:17], 0x80
	s_and_b32 s13, s10, 0x60
	s_add_i32 m0, s36, 0x18000
	v_lshl_add_u64 v[6:7], v[6:7], 0, s[16:17]
	s_lshl_b32 s12, s8, 13
	s_lshl_b32 s18, s13, 7
	s_waitcnt vmcnt(2)
	s_barrier
	global_load_lds_dwordx4 v[6:7], off
	v_lshl_add_u64 v[4:5], v[4:5], 0, s[16:17]
	s_add_i32 m0, s36, 0x1a000
	s_add_i32 s41, s36, 0x8000
	s_add_i32 s42, s36, 0xa000
	global_load_lds_dwordx4 v[4:5], off
	v_lshl_add_u64 v[2:3], v[2:3], 0, s[16:17]
	s_mov_b32 m0, s41
	s_add_u32 s10, s28, 0xb0080
	global_load_lds_dwordx4 v[2:3], off
	v_lshl_add_u64 v[0:1], v[0:1], 0, s[16:17]
	s_mov_b32 m0, s42
	s_addc_u32 s11, s29, 0
	global_load_lds_dwordx4 v[0:1], off
	s_add_i32 m0, s36, 0x1c000
	v_lshl_add_u64 v[0:1], s[10:11], 0, v[128:129]
	global_load_lds_dwordx4 v[0:1], off
	v_lshl_add_u64 v[0:1], s[10:11], 0, v[130:131]
	s_add_i32 m0, s36, 0x1e000
	s_mov_b64 s[10:11], 0xb0080
	global_load_lds_dwordx4 v[0:1], off
	v_bfe_u32 v0, v8, 4, 2
	v_and_b32_e32 v1, 15, v8
	v_lshlrev_b32_e32 v2, 4, v0
	v_lshl_or_b32 v146, s8, 6, v1
	v_lshl_or_b32 v1, v1, 6, v2
	v_lshlrev_b32_e32 v2, 2, v8
	v_and_b32_e32 v2, 32, v2
	v_bitop3_b32 v3, v1, s12, v2 bitop3:0xde
	v_bitop3_b32 v147, v1, s18, v2 bitop3:0xde
	v_lshl_or_b32 v148, v0, 2, s13
	v_lshrrev_b32_e32 v1, 1, v9
	v_mul_lo_u32 v0, v11, s9
	s_mov_b32 s8, 0xb000
	v_mad_u64_u32 v[0:1], s[12:13], v1, s8, v[0:1]
	v_or_b32_e32 v0, v0, v10
	v_add_lshl_u32 v0, v0, v12, 1
	v_mov_b32_e32 v1, v129
	v_lshl_add_u64 v[132:133], v[0:1], 0, s[10:11]
	v_lshrrev_b32_e32 v1, 1, v13
	v_mul_lo_u32 v0, v14, s9
	v_mad_u64_u32 v[0:1], s[8:9], v1, s8, v[0:1]
	s_waitcnt vmcnt(6)
	v_or_b32_e32 v0, v0, v15
	v_add_lshl_u32 v0, v0, v16, 1
	v_mov_b32_e32 v1, v129
	s_add_i32 s43, 0, 0x10000
	s_add_i32 s44, 0, 0x14000
	v_lshl_add_u64 v[134:135], v[0:1], 0, s[10:11]
	v_mov_b64_e32 v[136:137], 0x200
	v_mov_b64_e32 v[138:139], 0x1ff
	v_add_u32_e32 v149, s43, v147
	v_add_u32_e32 v150, 0, v3
	v_add_u32_e32 v151, s44, v147
	s_mov_b64 s[18:19], 0x80000
	s_mov_b64 s[22:23], 0x90000
	s_mov_b64 s[24:25], 0xa0000
	s_barrier

; __device__ __forceinline__ void s5_phase(const Params& P, const bf16_t* hn, bf16_t* ys, LAS unsigned char* lds) {
;     ...
;         for (int c = 0; c < SEQ / 32; ++c) {
;             const int t0 = c * 32;
;             const bf16x8 uf = ufn; const u32x2 uwc[2] = {uwn[0], uwn[1]};
;             { const int tn = (c + 1 < SEQ / 32) ? t0 + 32 : t0;
;               ufn = *(const bf16x8*)(hb + (size_t)(tn + c32) * D + 8 * hf);
; #pragma unroll
;               for (int tb = 0; tb < 2; ++tb) uwn[tb] = *(const u32x2*)(hb + (size_t)(tn + tb * 16 + c16) * D + 4 * q4); }
;             const f32x16 z16 = {0.f, 0.f, 0.f, 0.f, 0.f, 0.f, 0.f, 0.f, 0.f, 0.f, 0.f, 0.f, 0.f, 0.f, 0.f, 0.f};
;             f32x16 r0 = __builtin_amdgcn_mfma_f32_32x32x16_bf16(uf, Bre[0], z16, 0, 0, 0), r1 = __builtin_amdgcn_mfma_f32_32x32x16_bf16(uf, Bre[1], z16, 0, 0, 0);
;             f32x16 i0 = __builtin_amdgcn_mfma_f32_32x32x16_bf16(uf, Bim[0], z16, 0, 0, 0), i1 = __builtin_amdgcn_mfma_f32_32x32x16_bf16(uf, Bim[1], z16, 0, 0, 0);
; #pragma unroll
;             for (int q = 0; q < 4; ++q) {
;                 float xr[8], xi[8];
; #pragma unroll
;                 for (int i = 0; i < 4; ++i) {
;                     auto pr = __builtin_amdgcn_permlane32_swap(__float_as_uint(r0[4 * q + i]), __float_as_uint(r1[4 * q + i]), false, false);
;                     auto pi = __builtin_amdgcn_permlane32_swap(__float_as_uint(i0[4 * q + i]), __float_as_uint(i1[4 * q + i]), false, false);
;                     xr[i] = __uint_as_float(pr[0]); xr[4 + i] = __uint_as_float(pr[1]); xi[i] = __uint_as_float(pi[0]); xi[4 + i] = __uint_as_float(pi[1]); }
; #pragma unroll
;                 for (int i = 0; i < 8; ++i) { const float nr = ar * sr - ai * si + xr[i], ni = ar * si + ai * sr + xi[i]; sr = nr; si = ni;
;                     S[(8 * q + i) * 68 + lane] = cvt_pk_bf16(sr, si); }
.LBB0_551:
	v_mov_b64_e32 v[0:1], v[100:101]
	v_mov_b64_e32 v[2:3], v[102:103]
	v_lshl_add_u64 v[6:7], v[144:145], 0, s[8:9]
	v_lshl_add_u64 v[4:5], v[146:147], 0, s[8:9]
	global_load_dwordx4 v[100:103], v[6:7], off
	v_add_co_u32_e32 v6, vcc, 0x6010000, v4
	s_nop 1
	v_addc_co_u32_e32 v7, vcc, 0, v5, vcc
	v_add_co_u32_e32 v4, vcc, 0x6018000, v4
	s_nop 1
	v_addc_co_u32_e32 v5, vcc, 0, v5, vcc
	v_mov_b64_e32 v[150:151], v[140:141]
	v_lshlrev_b32_e32 v152, 16, v11
	v_and_b32_e32 v153, 0xffff0000, v11
	v_mfma_f32_32x32x16_bf16 v[48:63], v[0:3], v[84:87], 0
	v_lshlrev_b32_e32 v156, 16, v10
	v_and_b32_e32 v157, 0xffff0000, v10
	v_lshlrev_b32_e32 v158, 16, v149
	v_and_b32_e32 v159, 0xffff0000, v149
	global_load_dwordx2 v[148:149], v[6:7], off
	global_load_dwordx2 v[140:141], v[4:5], off
	v_mfma_f32_32x32x16_bf16 v[16:31], v[0:3], v[96:99], 0
	v_add_u32_e32 v104, 0x400, v161
	v_add_u32_e32 v123, 0x800, v161
	v_add_u32_e32 v125, 0xc00, v161
	v_add_u32_e32 v127, 0x1000, v161
	v_add_u32_e32 v129, 0x1200, v161
	v_add_u32_e32 v150, 0x1400, v161
	v_add_u32_e32 v172, 0x1600, v161
	v_mfma_f32_32x32x16_bf16 v[32:47], v[0:3], v[88:91], 0
	s_nop 3
	v_permlane32_swap_b32_e32 v48, v16
	v_permlane32_swap_b32_e32 v49, v17
	v_permlane32_swap_b32_e32 v50, v18
	v_permlane32_swap_b32_e32 v51, v19
	v_mfma_f32_32x32x16_bf16 v[0:15], v[0:3], v[92:95], 0
	v_permlane32_swap_b32_e32 v52, v20
	v_permlane32_swap_b32_e32 v53, v21
	v_permlane32_swap_b32_e32 v54, v22
	v_permlane32_swap_b32_e32 v55, v23
	s_nop 7
	v_permlane32_swap_b32_e32 v32, v0
	v_permlane32_swap_b32_e32 v34, v2
	v_permlane32_swap_b32_e32 v36, v4
	v_permlane32_swap_b32_e32 v38, v6
	v_permlane32_swap_b32_e32 v56, v24
	v_permlane32_swap_b32_e32 v40, v8
	v_permlane32_swap_b32_e32 v57, v25
	v_permlane32_swap_b32_e32 v58, v26
	v_permlane32_swap_b32_e32 v42, v10
	v_permlane32_swap_b32_e32 v59, v27
	v_permlane32_swap_b32_e32 v44, v12
	v_permlane32_swap_b32_e32 v61, v29
	v_permlane32_swap_b32_e32 v45, v13
	v_permlane32_swap_b32_e32 v62, v30
	v_permlane32_swap_b32_e32 v46, v14
	v_permlane32_swap_b32_e32 v63, v31
	v_permlane32_swap_b32_e32 v60, v28
	v_permlane32_swap_b32_e32 v33, v1
	v_permlane32_swap_b32_e32 v35, v3
	v_permlane32_swap_b32_e32 v37, v5
	v_permlane32_swap_b32_e32 v39, v7
	v_permlane32_swap_b32_e32 v41, v9
	v_permlane32_swap_b32_e32 v43, v11
	v_permlane32_swap_b32_e32 v47, v15
	v_xor_b32_e32 v182, 0x80000000, v136
	v_fmac_f32_e32 v48, v132, v138
	v_fmac_f32_e32 v32, v132, v139
	v_fmac_f32_e32 v48, v182, v139
	v_fmac_f32_e32 v32, v136, v138
	v_fmac_f32_e32 v49, v132, v48
	v_fmac_f32_e32 v33, v132, v32
	v_cvt_pk_bf16_f32 v183, v48, v32
	v_fmac_f32_e32 v49, v182, v32
	v_fmac_f32_e32 v33, v136, v48
	ds_write_b32 v161, v183 offset:0
	v_fmac_f32_e32 v50, v132, v49
	v_fmac_f32_e32 v34, v132, v33
	v_cvt_pk_bf16_f32 v184, v49, v33
	v_fmac_f32_e32 v50, v182, v33
	v_fmac_f32_e32 v34, v136, v49
	ds_write_b32 v161, v184 offset:272
	v_fmac_f32_e32 v51, v132, v50
	v_fmac_f32_e32 v35, v132, v34
	v_cvt_pk_bf16_f32 v185, v50, v34
	v_fmac_f32_e32 v51, v182, v34
	v_fmac_f32_e32 v35, v136, v50
	ds_write_b32 v161, v185 offset:544
	v_fmac_f32_e32 v16, v132, v51
	v_fmac_f32_e32 v0, v132, v35
	v_cvt_pk_bf16_f32 v186, v51, v35
	v_fmac_f32_e32 v16, v182, v35
	v_fmac_f32_e32 v0, v136, v51
	ds_write_b32 v161, v186 offset:816
	v_fmac_f32_e32 v17, v132, v16
	v_fmac_f32_e32 v1, v132, v0
	v_cvt_pk_bf16_f32 v183, v16, v0
	v_fmac_f32_e32 v17, v182, v0
	v_fmac_f32_e32 v1, v136, v16
	ds_write_b32 v161, v183 offset:1088
	v_fmac_f32_e32 v18, v132, v17
	v_fmac_f32_e32 v2, v132, v1
	v_cvt_pk_bf16_f32 v184, v17, v1
	v_fmac_f32_e32 v18, v182, v1
	v_fmac_f32_e32 v2, v136, v17
	ds_write_b32 v161, v184 offset:1360
	v_fmac_f32_e32 v19, v132, v18
	v_fmac_f32_e32 v3, v132, v2
	v_cvt_pk_bf16_f32 v185, v18, v2
	v_fmac_f32_e32 v19, v182, v2
	v_fmac_f32_e32 v3, v136, v18
	ds_write_b32 v161, v185 offset:1632
	v_fmac_f32_e32 v52, v132, v19
	v_fmac_f32_e32 v36, v132, v3
	v_cvt_pk_bf16_f32 v186, v19, v3
	v_fmac_f32_e32 v52, v182, v3
	v_fmac_f32_e32 v36, v136, v19
	ds_write_b32 v161, v186 offset:1904
	v_fmac_f32_e32 v53, v132, v52
	v_fmac_f32_e32 v37, v132, v36
	v_cvt_pk_bf16_f32 v183, v52, v36
	v_fmac_f32_e32 v53, v182, v36
	v_fmac_f32_e32 v37, v136, v52
	ds_write_b32 v161, v183 offset:2176
	v_fmac_f32_e32 v54, v132, v53
	v_fmac_f32_e32 v38, v132, v37
	v_cvt_pk_bf16_f32 v184, v53, v37
	v_fmac_f32_e32 v54, v182, v37
	v_fmac_f32_e32 v38, v136, v53
	ds_write_b32 v161, v184 offset:2448
	v_fmac_f32_e32 v55, v132, v54
	v_fmac_f32_e32 v39, v132, v38
	v_cvt_pk_bf16_f32 v185, v54, v38
	v_fmac_f32_e32 v55, v182, v38
	v_fmac_f32_e32 v39, v136, v54
	ds_write_b32 v161, v185 offset:2720
	v_fmac_f32_e32 v20, v132, v55
	v_fmac_f32_e32 v4, v132, v39
	v_cvt_pk_bf16_f32 v186, v55, v39
	v_fmac_f32_e32 v20, v182, v39
	v_fmac_f32_e32 v4, v136, v55
	ds_write_b32 v161, v186 offset:2992
	v_fmac_f32_e32 v21, v132, v20
	v_fmac_f32_e32 v5, v132, v4
	v_cvt_pk_bf16_f32 v183, v20, v4
	v_fmac_f32_e32 v21, v182, v4
	v_fmac_f32_e32 v5, v136, v20
	ds_write_b32 v161, v183 offset:3264
	v_fmac_f32_e32 v22, v132, v21
	v_fmac_f32_e32 v6, v132, v5
	v_cvt_pk_bf16_f32 v184, v21, v5
	v_fmac_f32_e32 v22, v182, v5
	v_fmac_f32_e32 v6, v136, v21
	ds_write_b32 v161, v184 offset:3536
	v_fmac_f32_e32 v23, v132, v22
	v_fmac_f32_e32 v7, v132, v6
	v_cvt_pk_bf16_f32 v185, v22, v6
	v_fmac_f32_e32 v23, v182, v6
	v_fmac_f32_e32 v7, v136, v22
	ds_write_b32 v161, v185 offset:3808
	v_fmac_f32_e32 v56, v132, v23
	v_fmac_f32_e32 v40, v132, v7
	v_cvt_pk_bf16_f32 v186, v23, v7
	v_fmac_f32_e32 v56, v182, v7
	v_fmac_f32_e32 v40, v136, v23
	ds_write_b32 v161, v186 offset:4080
	v_fmac_f32_e32 v57, v132, v56
	v_fmac_f32_e32 v41, v132, v40
; #define LAS __attribute__((address_space(3)))
; __device__ __forceinline__ float bflo(unsigned w) { return __uint_as_float(w << 16); }
; __device__ __forceinline__ float bfhi(unsigned w) { return __uint_as_float(w & 0xffff0000u); }
; __device__ __forceinline__ float gelu_tanh(float x) { const float k = 1.5957691216f * (x + 0.044715f * x * x * x); return x * __builtin_amdgcn_rcpf(1.0f + __expf(-k)); }
; __device__ __forceinline__ void s5_phase(const Params& P, const bf16_t* hn, bf16_t* ys, LAS unsigned char* lds) {
;     ...
;                 for (int i = 0; i < 8; ++i) { const float nr = ar * sr - ai * si + xr[i], ni = ar * si + ai * sr + xi[i]; sr = nr; si = ni;
;                     S[(8 * q + i) * 68 + lane] = cvt_pk_bf16(sr, si); }
;             }
;             asm volatile("" ::: "memory");
; #pragma unroll
;             for (int tb = 0; tb < 2; ++tb) {
;                 f32x4 y = (f32x4){0.f, 0.f, 0.f, 0.f};
; #pragma unroll
;                 for (int kb = 0; kb < 4; ++kb) { const bf16x8 sf = __builtin_bit_cast(bf16x8, *(const LAS u32x4*)(S + (tb * 16 + c16) * 68 + kb * 16 + 4 * q4));
;                     y = __builtin_amdgcn_mfma_f32_16x16x32_bf16(Cf[kb], sf, y, 0, 0, 0); }
;                 const size_t off = (size_t)(t0 + tb * 16 + c16) * D + 4 * q4;
;                 const u32x2 uw = uwc[tb];
;                 const float u0 = bflo(uw.x), u1 = bfhi(uw.x), u2 = bflo(uw.y), u3 = bfhi(uw.y);
;                 u32x2 w; w.x = cvt_pk_bf16(gelu_tanh(y[0] + dk[0] * u0), gelu_tanh(y[1] + dk[1] * u1)); w.y = cvt_pk_bf16(gelu_tanh(y[2] + dk[2] * u2), gelu_tanh(y[3] + dk[3] * u3));
;                 *(u32x2*)(yb + off) = w;
	v_cvt_pk_bf16_f32 v183, v56, v40
	v_fmac_f32_e32 v57, v182, v40
	v_fmac_f32_e32 v41, v136, v56
	ds_write_b32 v161, v183 offset:4352
	v_fmac_f32_e32 v58, v132, v57
	v_fmac_f32_e32 v42, v132, v41
	v_cvt_pk_bf16_f32 v184, v57, v41
	v_fmac_f32_e32 v58, v182, v41
	v_fmac_f32_e32 v42, v136, v57
	ds_write_b32 v161, v184 offset:4624
	v_fmac_f32_e32 v59, v132, v58
	v_fmac_f32_e32 v43, v132, v42
	v_cvt_pk_bf16_f32 v185, v58, v42
	v_fmac_f32_e32 v59, v182, v42
	v_fmac_f32_e32 v43, v136, v58
	ds_write_b32 v161, v185 offset:4896
	v_fmac_f32_e32 v24, v132, v59
	v_fmac_f32_e32 v8, v132, v43
	v_cvt_pk_bf16_f32 v186, v59, v43
	v_fmac_f32_e32 v24, v182, v43
	v_fmac_f32_e32 v8, v136, v59
	ds_write_b32 v161, v186 offset:5168
	v_fmac_f32_e32 v25, v132, v24
	v_fmac_f32_e32 v9, v132, v8
	v_cvt_pk_bf16_f32 v183, v24, v8
	v_fmac_f32_e32 v25, v182, v8
	v_fmac_f32_e32 v9, v136, v24
	ds_write_b32 v161, v183 offset:5440
	v_fmac_f32_e32 v26, v132, v25
	v_fmac_f32_e32 v10, v132, v9
	v_cvt_pk_bf16_f32 v184, v25, v9
	v_fmac_f32_e32 v26, v182, v9
	v_fmac_f32_e32 v10, v136, v25
	ds_write_b32 v161, v184 offset:5712
	v_fmac_f32_e32 v27, v132, v26
	v_fmac_f32_e32 v11, v132, v10
	v_cvt_pk_bf16_f32 v185, v26, v10
	v_fmac_f32_e32 v27, v182, v10
	v_fmac_f32_e32 v11, v136, v26
	ds_write_b32 v161, v185 offset:5984
	v_fmac_f32_e32 v60, v132, v27
	v_fmac_f32_e32 v44, v132, v11
	v_cvt_pk_bf16_f32 v186, v27, v11
	v_fmac_f32_e32 v60, v182, v11
	v_fmac_f32_e32 v44, v136, v27
	ds_write_b32 v161, v186 offset:6256
	v_fmac_f32_e32 v61, v132, v60
	v_fmac_f32_e32 v45, v132, v44
	v_cvt_pk_bf16_f32 v183, v60, v44
	v_fmac_f32_e32 v61, v182, v44
	v_fmac_f32_e32 v45, v136, v60
	ds_write_b32 v161, v183 offset:6528
	v_fmac_f32_e32 v62, v132, v61
	v_fmac_f32_e32 v46, v132, v45
	v_cvt_pk_bf16_f32 v184, v61, v45
	v_fmac_f32_e32 v62, v182, v45
	v_fmac_f32_e32 v46, v136, v61
	ds_write_b32 v161, v184 offset:6800
	v_fmac_f32_e32 v63, v132, v62
	v_fmac_f32_e32 v47, v132, v46
	v_cvt_pk_bf16_f32 v185, v62, v46
	v_fmac_f32_e32 v63, v182, v46
	v_fmac_f32_e32 v47, v136, v62
	ds_write_b32 v161, v185 offset:7072
	v_fmac_f32_e32 v28, v132, v63
	v_fmac_f32_e32 v12, v132, v47
	v_cvt_pk_bf16_f32 v186, v63, v47
	v_fmac_f32_e32 v28, v182, v47
	v_fmac_f32_e32 v12, v136, v63
	ds_write_b32 v161, v186 offset:7344
	v_fmac_f32_e32 v29, v132, v28
	v_fmac_f32_e32 v13, v132, v12
	v_cvt_pk_bf16_f32 v183, v28, v12
	v_fmac_f32_e32 v29, v182, v12
	v_fmac_f32_e32 v13, v136, v28
	ds_write_b32 v161, v183 offset:7616
	v_fmac_f32_e32 v30, v132, v29
	v_fmac_f32_e32 v14, v132, v13
	v_cvt_pk_bf16_f32 v184, v29, v13
	v_fmac_f32_e32 v30, v182, v13
	v_fmac_f32_e32 v14, v136, v29
	ds_write_b32 v161, v184 offset:7888
	v_fmac_f32_e32 v31, v132, v30
	v_fmac_f32_e32 v15, v132, v14
	v_cvt_pk_bf16_f32 v185, v30, v14
	v_fmac_f32_e32 v31, v182, v14
	v_fmac_f32_e32 v15, v136, v30
	ds_write_b32 v161, v185 offset:8160
	v_cvt_pk_bf16_f32 v186, v31, v15
	v_mov_b32_e32 v138, v31
	v_mov_b32_e32 v139, v15
	ds_write_b32 v161, v186 offset:8432
	v_add_u32_e32 v173, 0x1800, v161
	v_add_u32_e32 v174, 0x1a00, v161
	v_add_u32_e32 v176, 0x1c00, v161
	v_add_u32_e32 v175, 0x1e00, v161
	v_lshl_add_u64 v[154:155], v[142:143], 0, s[8:9]
	s_add_u32 s8, s8, 0x10000
	s_addc_u32 s9, s9, 0
	s_cmp_eq_u32 s8, 0x3f0000
	v_add_co_u32_e32 v20, vcc, s63, v154
	s_nop 1
	v_addc_co_u32_e32 v21, vcc, 0, v155, vcc
	v_lshlrev_b32_e32 v22, 16, v151
	v_and_b32_e32 v23, 0xffff0000, v151
	ds_read_b128 v[0:3], v171
	ds_read_b128 v[4:7], v171 offset:64
	ds_read_b128 v[8:11], v171 offset:4352
	ds_read_b128 v[12:15], v171 offset:4416
	s_waitcnt lgkmcnt(3)
	v_mfma_f32_16x16x32_bf16 v[0:3], v[80:83], v[0:3], 0
	s_waitcnt lgkmcnt(1)
	v_mfma_f32_16x16x32_bf16 v[8:11], v[80:83], v[8:11], 0
	v_mfma_f32_16x16x32_bf16 v[0:3], v[76:79], v[4:7], v[0:3]
	s_waitcnt lgkmcnt(0)
	v_mfma_f32_16x16x32_bf16 v[4:7], v[76:79], v[12:15], v[8:11]
	s_nop 4
	ds_read_b128 v[8:11], v171 offset:128
	ds_read_b128 v[12:15], v171 offset:192
	s_waitcnt lgkmcnt(1)
	v_mfma_f32_16x16x32_bf16 v[0:3], v[72:75], v[8:11], v[0:3]
	ds_read_b128 v[8:11], v171 offset:4480
	ds_read_b128 v[16:19], v171 offset:4544
	s_waitcnt lgkmcnt(1)
	v_mfma_f32_16x16x32_bf16 v[4:7], v[72:75], v[8:11], v[4:7]
	v_add_co_u32_e32 v8, vcc, s68, v154
	s_waitcnt vmcnt(1)
	v_mov_b32_e32 v11, v148
	v_mfma_f32_16x16x32_bf16 v[0:3], v[68:71], v[12:15], v[0:3]
	s_waitcnt vmcnt(0)
	v_mov_b32_e32 v10, v140
	v_addc_co_u32_e32 v9, vcc, 0, v155, vcc
	s_waitcnt lgkmcnt(0)
	v_mfma_f32_16x16x32_bf16 v[4:7], v[68:71], v[16:19], v[4:7]
	s_nop 2
	v_fma_f32 v0, v64, v152, v0
	v_fma_f32 v1, v65, v153, v1
	v_pk_fma_f32 v[2:3], v[66:67], v[158:159], v[2:3]
	s_nop 1
	v_pk_fma_f32 v[4:5], v[64:65], v[156:157], v[4:5]
	v_pk_fma_f32 v[6:7], v[66:67], v[22:23], v[6:7]
	v_mul_f32_e32 v12, 0x3d372713, v0
	v_mul_f32_e32 v13, 0x3d372713, v1
	v_mul_f32_e32 v14, 0x3d372713, v2
	v_mul_f32_e32 v15, 0x3d372713, v3
	v_mul_f32_e32 v16, 0x3d372713, v4
	v_mul_f32_e32 v17, 0x3d372713, v5
	v_mul_f32_e32 v18, 0x3d372713, v6
	v_mul_f32_e32 v19, 0x3d372713, v7
	v_mul_f32_e32 v12, v0, v12
	v_mul_f32_e32 v13, v1, v13
	v_mul_f32_e32 v14, v2, v14
	v_mul_f32_e32 v15, v3, v15
	v_mul_f32_e32 v16, v4, v16
	v_mul_f32_e32 v17, v5, v17
	v_mul_f32_e32 v18, v6, v18
	v_mul_f32_e32 v19, v7, v19
	v_fma_f32 v12, v0, v12, v0
	v_fma_f32 v13, v1, v13, v1
	v_fma_f32 v14, v2, v14, v2
	v_fma_f32 v15, v3, v15, v3
	v_fma_f32 v16, v4, v16, v4
	v_fma_f32 v17, v5, v17, v5
	v_fma_f32 v18, v6, v18, v6
	v_fma_f32 v19, v7, v19, v7
	v_mul_f32_e32 v12, 0xbfcc422a, v12
	v_mul_f32_e32 v13, 0xbfcc422a, v13
	v_mul_f32_e32 v14, 0xbfcc422a, v14
	v_mul_f32_e32 v15, 0xbfcc422a, v15
	v_mul_f32_e32 v16, 0xbfcc422a, v16
	v_mul_f32_e32 v17, 0xbfcc422a, v17
	v_mul_f32_e32 v18, 0xbfcc422a, v18
	v_mul_f32_e32 v19, 0xbfcc422a, v19
	v_mul_f32_e32 v12, 0x3fb8aa3b, v12
	v_mul_f32_e32 v13, 0x3fb8aa3b, v13
	v_mul_f32_e32 v14, 0x3fb8aa3b, v14
	v_mul_f32_e32 v15, 0x3fb8aa3b, v15
	v_mul_f32_e32 v16, 0x3fb8aa3b, v16
	v_mul_f32_e32 v17, 0x3fb8aa3b, v17
	v_mul_f32_e32 v18, 0x3fb8aa3b, v18
	v_mul_f32_e32 v19, 0x3fb8aa3b, v19
	v_exp_f32_e32 v12, v12
	v_exp_f32_e32 v13, v13
	v_exp_f32_e32 v14, v14
	v_exp_f32_e32 v15, v15
	v_exp_f32_e32 v16, v16
	v_exp_f32_e32 v17, v17
	v_exp_f32_e32 v18, v18
	v_exp_f32_e32 v19, v19
	v_add_f32_e32 v12, 1.0, v12
	v_add_f32_e32 v13, 1.0, v13
	v_add_f32_e32 v14, 1.0, v14
	v_add_f32_e32 v15, 1.0, v15
	v_add_f32_e32 v16, 1.0, v16
	v_add_f32_e32 v17, 1.0, v17
	v_add_f32_e32 v18, 1.0, v18
	v_add_f32_e32 v19, 1.0, v19
	v_rcp_f32_e32 v12, v12
	v_rcp_f32_e32 v13, v13
	v_rcp_f32_e32 v14, v14
	v_rcp_f32_e32 v15, v15
	v_rcp_f32_e32 v16, v16
	v_rcp_f32_e32 v17, v17
	v_rcp_f32_e32 v18, v18
	v_rcp_f32_e32 v19, v19
	v_pk_mul_f32 v[0:1], v[0:1], v[12:13]
	v_pk_mul_f32 v[2:3], v[2:3], v[14:15]
	v_pk_mul_f32 v[4:5], v[4:5], v[16:17]
	v_pk_mul_f32 v[6:7], v[6:7], v[18:19]
	v_cvt_pk_bf16_f32 v0, v0, v1
	v_cvt_pk_bf16_f32 v1, v2, v3
	v_cvt_pk_bf16_f32 v2, v4, v5
	v_cvt_pk_bf16_f32 v3, v6, v7
	global_store_dwordx2 v[20:21], v[0:1], off
	global_store_dwordx2 v[8:9], v[2:3], off
	s_cbranch_scc0 .LBB0_551
; __device__ __forceinline__ void s5_phase(const Params& P, const bf16_t* hn, bf16_t* ys, LAS unsigned char* lds) {
;     ...
;             f32x16 r0 = __builtin_amdgcn_mfma_f32_32x32x16_bf16(uf, Bre[0], z16, 0, 0, 0), r1 = __builtin_amdgcn_mfma_f32_32x32x16_bf16(uf, Bre[1], z16, 0, 0, 0);
;             f32x16 i0 = __builtin_amdgcn_mfma_f32_32x32x16_bf16(uf, Bim[0], z16, 0, 0, 0), i1 = __builtin_amdgcn_mfma_f32_32x32x16_bf16(uf, Bim[1], z16, 0, 0, 0);
; #pragma unroll
;             for (int q = 0; q < 4; ++q) {
;                 float xr[8], xi[8];
; #pragma unroll
;                 for (int i = 0; i < 4; ++i) {
;                     auto pr = __builtin_amdgcn_permlane32_swap(__float_as_uint(r0[4 * q + i]), __float_as_uint(r1[4 * q + i]), false, false);
;                     auto pi = __builtin_amdgcn_permlane32_swap(__float_as_uint(i0[4 * q + i]), __float_as_uint(i1[4 * q + i]), false, false);
;                     xr[i] = __uint_as_float(pr[0]); xr[4 + i] = __uint_as_float(pr[1]); xi[i] = __uint_as_float(pi[0]); xi[4 + i] = __uint_as_float(pi[1]); }
; #pragma unroll
;                 for (int i = 0; i < 8; ++i) { const float nr = ar * sr - ai * si + xr[i], ni = ar * si + ai * sr + xi[i]; sr = nr; si = ni;
;                     S[(8 * q + i) * 68 + lane] = cvt_pk_bf16(sr, si); }
	v_mfma_f32_32x32x16_bf16 v[48:63], v[100:103], v[84:87], 0
	v_mul_f32_e64 v84, v136, v138
	v_mul_f32_e64 v85, v137, v139
	v_add_u32_e32 v131, s4, v131
	v_add_u16_e32 v162, s4, v162
	v_mfma_f32_32x32x16_bf16 v[16:31], v[100:103], v[96:99], 0
	v_mfma_f32_32x32x16_bf16 v[32:47], v[100:103], v[88:91], 0
	s_nop 10
	v_permlane32_swap_b32_e32 v48, v16
	v_fma_f32 v88, v132, v138, -v85
	v_fma_f32 v89, v133, v139, -v84
	v_pk_fma_f32 v[84:85], v[132:133], v[138:139], v[84:85] op_sel:[0,0,1] op_sel_hi:[1,1,0]
	v_mov_b32_e32 v86, v48
	v_mov_b32_e32 v89, v85
	v_permlane32_swap_b32_e32 v49, v17
	v_mfma_f32_32x32x16_bf16 v[0:15], v[100:103], v[92:95], 0
	v_permlane32_swap_b32_e32 v50, v18
	v_permlane32_swap_b32_e32 v51, v19
	v_permlane32_swap_b32_e32 v52, v20
	v_permlane32_swap_b32_e32 v53, v21
	s_nop 7
	v_permlane32_swap_b32_e32 v32, v0
	v_mov_b32_e32 v87, v32
	v_pk_add_f32 v[84:85], v[88:89], v[86:87]
	v_mov_b32_e32 v32, v49
	v_pk_mul_f32 v[48:49], v[136:137], v[84:85]
	v_permlane32_swap_b32_e32 v33, v1
	v_pk_fma_f32 v[86:87], v[132:133], v[84:85], v[48:49] op_sel:[0,0,1] op_sel_hi:[1,1,0] neg_lo:[0,0,1] neg_hi:[0,0,1]
	v_pk_fma_f32 v[48:49], v[132:133], v[84:85], v[48:49] op_sel:[0,0,1] op_sel_hi:[1,1,0]
	v_cvt_pk_bf16_f32 v88, v84, v85
	v_mov_b32_e32 v87, v49
	v_pk_add_f32 v[32:33], v[86:87], v[32:33]
	v_permlane32_swap_b32_e32 v34, v2
	v_pk_mul_f32 v[84:85], v[136:137], v[32:33]
	v_cvt_pk_bf16_f32 v48, v32, v33
	v_pk_fma_f32 v[86:87], v[132:133], v[32:33], v[84:85] op_sel:[0,0,1] op_sel_hi:[1,1,0] neg_lo:[0,0,1] neg_hi:[0,0,1]
	v_pk_fma_f32 v[32:33], v[132:133], v[32:33], v[84:85] op_sel:[0,0,1] op_sel_hi:[1,1,0]
	ds_write2_b32 v161, v88, v48 offset1:68
	v_mov_b32_e32 v48, v50
	v_mov_b32_e32 v49, v34
	v_mov_b32_e32 v87, v33
	v_pk_add_f32 v[32:33], v[86:87], v[48:49]
	v_mov_b32_e32 v34, v51
	v_pk_mul_f32 v[48:49], v[136:137], v[32:33]
	v_cvt_pk_bf16_f32 v84, v32, v33
	v_pk_fma_f32 v[50:51], v[132:133], v[32:33], v[48:49] op_sel:[0,0,1] op_sel_hi:[1,1,0] neg_lo:[0,0,1] neg_hi:[0,0,1]
	v_pk_fma_f32 v[32:33], v[132:133], v[32:33], v[48:49] op_sel:[0,0,1] op_sel_hi:[1,1,0]
	v_permlane32_swap_b32_e32 v35, v3
	v_mov_b32_e32 v51, v33
	v_pk_add_f32 v[32:33], v[50:51], v[34:35]
	v_mov_b32_e32 v35, v0
	v_pk_mul_f32 v[48:49], v[136:137], v[32:33]
	v_cvt_pk_bf16_f32 v34, v32, v33
	v_pk_fma_f32 v[50:51], v[132:133], v[32:33], v[48:49] op_sel:[0,0,1] op_sel_hi:[1,1,0] neg_lo:[0,0,1] neg_hi:[0,0,1]
	v_pk_fma_f32 v[32:33], v[132:133], v[32:33], v[48:49] op_sel:[0,0,1] op_sel_hi:[1,1,0]
	ds_write2_b32 v161, v84, v34 offset0:136 offset1:204
	v_mov_b32_e32 v34, v16
	v_mov_b32_e32 v51, v33
	v_pk_add_f32 v[32:33], v[50:51], v[34:35]
	v_mov_b32_e32 v0, v17
	v_pk_mul_f32 v[16:17], v[136:137], v[32:33]
	v_cvt_pk_bf16_f32 v48, v32, v33
	v_pk_fma_f32 v[34:35], v[132:133], v[32:33], v[16:17] op_sel:[0,0,1] op_sel_hi:[1,1,0] neg_lo:[0,0,1] neg_hi:[0,0,1]
	v_pk_fma_f32 v[16:17], v[132:133], v[32:33], v[16:17] op_sel:[0,0,1] op_sel_hi:[1,1,0]
	v_permlane32_swap_b32_e32 v36, v4
	v_mov_b32_e32 v35, v17
	v_pk_add_f32 v[0:1], v[34:35], v[0:1]
	v_mov_b32_e32 v17, v2
	v_pk_mul_f32 v[32:33], v[136:137], v[0:1]
	v_cvt_pk_bf16_f32 v16, v0, v1
	v_pk_fma_f32 v[34:35], v[132:133], v[0:1], v[32:33] op_sel:[0,0,1] op_sel_hi:[1,1,0] neg_lo:[0,0,1] neg_hi:[0,0,1]
	v_pk_fma_f32 v[0:1], v[132:133], v[0:1], v[32:33] op_sel:[0,0,1] op_sel_hi:[1,1,0]
	ds_write2_b32 v104, v48, v16 offset0:16 offset1:84
	v_mov_b32_e32 v16, v18
	v_mov_b32_e32 v35, v1
	v_pk_add_f32 v[0:1], v[34:35], v[16:17]
	v_mov_b32_e32 v2, v19
	v_pk_mul_f32 v[16:17], v[136:137], v[0:1]
	v_cvt_pk_bf16_f32 v32, v0, v1
	v_pk_fma_f32 v[18:19], v[132:133], v[0:1], v[16:17] op_sel:[0,0,1] op_sel_hi:[1,1,0] neg_lo:[0,0,1] neg_hi:[0,0,1]
	v_pk_fma_f32 v[0:1], v[132:133], v[0:1], v[16:17] op_sel:[0,0,1] op_sel_hi:[1,1,0]
	v_permlane32_swap_b32_e32 v37, v5
	v_mov_b32_e32 v19, v1
	v_pk_add_f32 v[0:1], v[18:19], v[2:3]
	v_mov_b32_e32 v3, v36
	v_pk_mul_f32 v[16:17], v[136:137], v[0:1]
	v_cvt_pk_bf16_f32 v2, v0, v1
	v_pk_fma_f32 v[18:19], v[132:133], v[0:1], v[16:17] op_sel:[0,0,1] op_sel_hi:[1,1,0] neg_lo:[0,0,1] neg_hi:[0,0,1]
	v_pk_fma_f32 v[0:1], v[132:133], v[0:1], v[16:17] op_sel:[0,0,1] op_sel_hi:[1,1,0]
	ds_write2_b32 v104, v32, v2 offset0:152 offset1:220
	v_mov_b32_e32 v2, v52
	v_mov_b32_e32 v19, v1
	v_pk_add_f32 v[0:1], v[18:19], v[2:3]
	v_mov_b32_e32 v36, v53
	v_pk_mul_f32 v[2:3], v[136:137], v[0:1]
	v_cvt_pk_bf16_f32 v18, v0, v1
	v_pk_fma_f32 v[16:17], v[132:133], v[0:1], v[2:3] op_sel:[0,0,1] op_sel_hi:[1,1,0] neg_lo:[0,0,1] neg_hi:[0,0,1]
	v_pk_fma_f32 v[0:1], v[132:133], v[0:1], v[2:3] op_sel:[0,0,1] op_sel_hi:[1,1,0]
	v_permlane32_swap_b32_e32 v54, v22
	v_mov_b32_e32 v17, v1
	v_pk_add_f32 v[0:1], v[16:17], v[36:37]
	v_permlane32_swap_b32_e32 v38, v6
	v_cvt_pk_bf16_f32 v2, v0, v1
	v_pk_mul_f32 v[16:17], v[136:137], v[0:1]
	ds_write2_b32 v123, v18, v2 offset0:32 offset1:100
	v_pk_fma_f32 v[18:19], v[132:133], v[0:1], v[16:17] op_sel:[0,0,1] op_sel_hi:[1,1,0] neg_lo:[0,0,1] neg_hi:[0,0,1]
	v_pk_fma_f32 v[0:1], v[132:133], v[0:1], v[16:17] op_sel:[0,0,1] op_sel_hi:[1,1,0]
	v_mov_b32_e32 v2, v54
	v_mov_b32_e32 v3, v38
	v_mov_b32_e32 v19, v1
	v_pk_add_f32 v[0:1], v[18:19], v[2:3]
	v_permlane32_swap_b32_e32 v55, v23
	v_pk_mul_f32 v[2:3], v[136:137], v[0:1]
	v_cvt_pk_bf16_f32 v18, v0, v1
	v_pk_fma_f32 v[16:17], v[132:133], v[0:1], v[2:3] op_sel:[0,0,1] op_sel_hi:[1,1,0] neg_lo:[0,0,1] neg_hi:[0,0,1]
	v_pk_fma_f32 v[0:1], v[132:133], v[0:1], v[2:3] op_sel:[0,0,1] op_sel_hi:[1,1,0]
	v_permlane32_swap_b32_e32 v39, v7
	v_mov_b32_e32 v38, v55
	v_mov_b32_e32 v17, v1
	v_pk_add_f32 v[0:1], v[16:17], v[38:39]
	v_mov_b32_e32 v3, v4
; __device__ __forceinline__ void s5_phase(const Params& P, const bf16_t* hn, bf16_t* ys, LAS unsigned char* lds) {
;     ...
;                 for (int i = 0; i < 8; ++i) { const float nr = ar * sr - ai * si + xr[i], ni = ar * si + ai * sr + xi[i]; sr = nr; si = ni;
;                     S[(8 * q + i) * 68 + lane] = cvt_pk_bf16(sr, si); }
	v_cvt_pk_bf16_f32 v2, v0, v1
	v_pk_mul_f32 v[16:17], v[136:137], v[0:1]
	ds_write2_b32 v123, v18, v2 offset0:168 offset1:236
	v_pk_fma_f32 v[18:19], v[132:133], v[0:1], v[16:17] op_sel:[0,0,1] op_sel_hi:[1,1,0] neg_lo:[0,0,1] neg_hi:[0,0,1]
	v_pk_fma_f32 v[0:1], v[132:133], v[0:1], v[16:17] op_sel:[0,0,1] op_sel_hi:[1,1,0]
	v_mov_b32_e32 v2, v20
	v_mov_b32_e32 v19, v1
	v_pk_add_f32 v[0:1], v[18:19], v[2:3]
	v_mov_b32_e32 v4, v21
	v_pk_mul_f32 v[2:3], v[136:137], v[0:1]
	v_cvt_pk_bf16_f32 v18, v0, v1
	v_pk_fma_f32 v[16:17], v[132:133], v[0:1], v[2:3] op_sel:[0,0,1] op_sel_hi:[1,1,0] neg_lo:[0,0,1] neg_hi:[0,0,1]
	v_pk_fma_f32 v[0:1], v[132:133], v[0:1], v[2:3] op_sel:[0,0,1] op_sel_hi:[1,1,0]
	v_mov_b32_e32 v3, v6
	v_mov_b32_e32 v17, v1
	v_pk_add_f32 v[0:1], v[16:17], v[4:5]
	v_mov_b32_e32 v6, v23
	v_pk_mul_f32 v[4:5], v[136:137], v[0:1]
	v_cvt_pk_bf16_f32 v2, v0, v1
	v_pk_fma_f32 v[16:17], v[132:133], v[0:1], v[4:5] op_sel:[0,0,1] op_sel_hi:[1,1,0] neg_lo:[0,0,1] neg_hi:[0,0,1]
	v_pk_fma_f32 v[0:1], v[132:133], v[0:1], v[4:5] op_sel:[0,0,1] op_sel_hi:[1,1,0]
	ds_write2_b32 v125, v18, v2 offset0:48 offset1:116
	v_mov_b32_e32 v2, v22
	v_mov_b32_e32 v17, v1
	v_pk_add_f32 v[0:1], v[16:17], v[2:3]
	v_permlane32_swap_b32_e32 v56, v24
	v_pk_mul_f32 v[2:3], v[136:137], v[0:1]
	v_cvt_pk_bf16_f32 v16, v0, v1
	v_pk_fma_f32 v[4:5], v[132:133], v[0:1], v[2:3] op_sel:[0,0,1] op_sel_hi:[1,1,0] neg_lo:[0,0,1] neg_hi:[0,0,1]
	v_pk_fma_f32 v[0:1], v[132:133], v[0:1], v[2:3] op_sel:[0,0,1] op_sel_hi:[1,1,0]
	v_permlane32_swap_b32_e32 v40, v8
	v_mov_b32_e32 v5, v1
	v_pk_add_f32 v[0:1], v[4:5], v[6:7]
	v_mov_b32_e32 v3, v40
	v_pk_mul_f32 v[4:5], v[136:137], v[0:1]
	v_cvt_pk_bf16_f32 v2, v0, v1
	v_pk_fma_f32 v[6:7], v[132:133], v[0:1], v[4:5] op_sel:[0,0,1] op_sel_hi:[1,1,0] neg_lo:[0,0,1] neg_hi:[0,0,1]
	v_pk_fma_f32 v[0:1], v[132:133], v[0:1], v[4:5] op_sel:[0,0,1] op_sel_hi:[1,1,0]
	ds_write2_b32 v125, v16, v2 offset0:184 offset1:252
	v_mov_b32_e32 v2, v56
	v_mov_b32_e32 v7, v1
	v_pk_add_f32 v[0:1], v[6:7], v[2:3]
	v_permlane32_swap_b32_e32 v57, v25
	v_pk_mul_f32 v[2:3], v[136:137], v[0:1]
	v_cvt_pk_bf16_f32 v6, v0, v1
	v_pk_fma_f32 v[4:5], v[132:133], v[0:1], v[2:3] op_sel:[0,0,1] op_sel_hi:[1,1,0] neg_lo:[0,0,1] neg_hi:[0,0,1]
	v_pk_fma_f32 v[0:1], v[132:133], v[0:1], v[2:3] op_sel:[0,0,1] op_sel_hi:[1,1,0]
	v_permlane32_swap_b32_e32 v41, v9
	v_mov_b32_e32 v40, v57
	v_mov_b32_e32 v5, v1
	v_pk_add_f32 v[0:1], v[4:5], v[40:41]
	v_permlane32_swap_b32_e32 v58, v26
	v_cvt_pk_bf16_f32 v2, v0, v1
	v_pk_mul_f32 v[4:5], v[136:137], v[0:1]
	v_permlane32_swap_b32_e32 v42, v10
	ds_write2_b32 v127, v6, v2 offset0:64 offset1:132
	v_pk_fma_f32 v[6:7], v[132:133], v[0:1], v[4:5] op_sel:[0,0,1] op_sel_hi:[1,1,0] neg_lo:[0,0,1] neg_hi:[0,0,1]
	v_pk_fma_f32 v[0:1], v[132:133], v[0:1], v[4:5] op_sel:[0,0,1] op_sel_hi:[1,1,0]
	v_mov_b32_e32 v2, v58
	v_mov_b32_e32 v3, v42
	v_mov_b32_e32 v7, v1
	v_pk_add_f32 v[0:1], v[6:7], v[2:3]
	v_permlane32_swap_b32_e32 v59, v27
	v_pk_mul_f32 v[2:3], v[136:137], v[0:1]
	v_cvt_pk_bf16_f32 v6, v0, v1
	v_pk_fma_f32 v[4:5], v[132:133], v[0:1], v[2:3] op_sel:[0,0,1] op_sel_hi:[1,1,0] neg_lo:[0,0,1] neg_hi:[0,0,1]
	v_pk_fma_f32 v[0:1], v[132:133], v[0:1], v[2:3] op_sel:[0,0,1] op_sel_hi:[1,1,0]
	v_permlane32_swap_b32_e32 v43, v11
	v_mov_b32_e32 v42, v59
	v_mov_b32_e32 v5, v1
	v_pk_add_f32 v[0:1], v[4:5], v[42:43]
	v_mov_b32_e32 v3, v8
	v_cvt_pk_bf16_f32 v2, v0, v1
	v_pk_mul_f32 v[4:5], v[136:137], v[0:1]
	ds_write2_b32 v129, v6, v2 offset0:72 offset1:140
	v_pk_fma_f32 v[6:7], v[132:133], v[0:1], v[4:5] op_sel:[0,0,1] op_sel_hi:[1,1,0] neg_lo:[0,0,1] neg_hi:[0,0,1]
	v_pk_fma_f32 v[0:1], v[132:133], v[0:1], v[4:5] op_sel:[0,0,1] op_sel_hi:[1,1,0]
	v_mov_b32_e32 v2, v24
	v_mov_b32_e32 v7, v1
	v_pk_add_f32 v[0:1], v[6:7], v[2:3]
	v_mov_b32_e32 v8, v25
	v_pk_mul_f32 v[2:3], v[136:137], v[0:1]
	v_cvt_pk_bf16_f32 v6, v0, v1
	v_pk_fma_f32 v[4:5], v[132:133], v[0:1], v[2:3] op_sel:[0,0,1] op_sel_hi:[1,1,0] neg_lo:[0,0,1] neg_hi:[0,0,1]
	v_pk_fma_f32 v[0:1], v[132:133], v[0:1], v[2:3] op_sel:[0,0,1] op_sel_hi:[1,1,0]
	v_mov_b32_e32 v3, v10
	v_mov_b32_e32 v5, v1
	v_pk_add_f32 v[0:1], v[4:5], v[8:9]
	v_mov_b32_e32 v10, v27
	v_cvt_pk_bf16_f32 v2, v0, v1
	v_pk_mul_f32 v[4:5], v[136:137], v[0:1]
	ds_write2_b32 v150, v6, v2 offset0:80 offset1:148
	v_pk_fma_f32 v[6:7], v[132:133], v[0:1], v[4:5] op_sel:[0,0,1] op_sel_hi:[1,1,0] neg_lo:[0,0,1] neg_hi:[0,0,1]
	v_pk_fma_f32 v[0:1], v[132:133], v[0:1], v[4:5] op_sel:[0,0,1] op_sel_hi:[1,1,0]
	v_mov_b32_e32 v2, v26
	v_mov_b32_e32 v7, v1
	v_pk_add_f32 v[0:1], v[6:7], v[2:3]
	v_permlane32_swap_b32_e32 v60, v28
	v_pk_mul_f32 v[2:3], v[136:137], v[0:1]
	v_cvt_pk_bf16_f32 v6, v0, v1
	v_pk_fma_f32 v[4:5], v[132:133], v[0:1], v[2:3] op_sel:[0,0,1] op_sel_hi:[1,1,0] neg_lo:[0,0,1] neg_hi:[0,0,1]
	v_pk_fma_f32 v[0:1], v[132:133], v[0:1], v[2:3] op_sel:[0,0,1] op_sel_hi:[1,1,0]
	v_permlane32_swap_b32_e32 v44, v12
	v_mov_b32_e32 v5, v1
	v_pk_add_f32 v[0:1], v[4:5], v[10:11]
	v_mov_b32_e32 v3, v44
	v_cvt_pk_bf16_f32 v2, v0, v1
	v_pk_mul_f32 v[4:5], v[136:137], v[0:1]
	ds_write2_b32 v172, v6, v2 offset0:88 offset1:156
	v_pk_fma_f32 v[6:7], v[132:133], v[0:1], v[4:5] op_sel:[0,0,1] op_sel_hi:[1,1,0] neg_lo:[0,0,1] neg_hi:[0,0,1]
	v_pk_fma_f32 v[0:1], v[132:133], v[0:1], v[4:5] op_sel:[0,0,1] op_sel_hi:[1,1,0]
	v_mov_b32_e32 v2, v60
	v_mov_b32_e32 v7, v1
	v_pk_add_f32 v[0:1], v[6:7], v[2:3]
	v_permlane32_swap_b32_e32 v61, v29
	v_pk_mul_f32 v[2:3], v[136:137], v[0:1]
	v_cvt_pk_bf16_f32 v6, v0, v1
	v_pk_fma_f32 v[4:5], v[132:133], v[0:1], v[2:3] op_sel:[0,0,1] op_sel_hi:[1,1,0] neg_lo:[0,0,1] neg_hi:[0,0,1]
; #define LAS __attribute__((address_space(3)))
; __device__ __forceinline__ float bflo(unsigned w) { return __uint_as_float(w << 16); }
; __device__ __forceinline__ float bfhi(unsigned w) { return __uint_as_float(w & 0xffff0000u); }
; __device__ __forceinline__ float gelu_tanh(float x) { const float k = 1.5957691216f * (x + 0.044715f * x * x * x); return x * __builtin_amdgcn_rcpf(1.0f + __expf(-k)); }
; __device__ __forceinline__ void s5_phase(const Params& P, const bf16_t* hn, bf16_t* ys, LAS unsigned char* lds) {
;     ...
;                 for (int i = 0; i < 8; ++i) { const float nr = ar * sr - ai * si + xr[i], ni = ar * si + ai * sr + xi[i]; sr = nr; si = ni;
;                     S[(8 * q + i) * 68 + lane] = cvt_pk_bf16(sr, si); }
;             }
;             asm volatile("" ::: "memory");
; #pragma unroll
;             for (int tb = 0; tb < 2; ++tb) {
;                 f32x4 y = (f32x4){0.f, 0.f, 0.f, 0.f};
; #pragma unroll
;                 for (int kb = 0; kb < 4; ++kb) { const bf16x8 sf = __builtin_bit_cast(bf16x8, *(const LAS u32x4*)(S + (tb * 16 + c16) * 68 + kb * 16 + 4 * q4));
;                     y = __builtin_amdgcn_mfma_f32_16x16x32_bf16(Cf[kb], sf, y, 0, 0, 0); }
;                 const size_t off = (size_t)(t0 + tb * 16 + c16) * D + 4 * q4;
;                 const u32x2 uw = uwc[tb];
;                 const float u0 = bflo(uw.x), u1 = bfhi(uw.x), u2 = bflo(uw.y), u3 = bfhi(uw.y);
;                 u32x2 w; w.x = cvt_pk_bf16(gelu_tanh(y[0] + dk[0] * u0), gelu_tanh(y[1] + dk[1] * u1)); w.y = cvt_pk_bf16(gelu_tanh(y[2] + dk[2] * u2), gelu_tanh(y[3] + dk[3] * u3));
;                 *(u32x2*)(yb + off) = w;
	v_pk_fma_f32 v[0:1], v[132:133], v[0:1], v[2:3] op_sel:[0,0,1] op_sel_hi:[1,1,0]
	v_permlane32_swap_b32_e32 v45, v13
	v_mov_b32_e32 v44, v61
	v_mov_b32_e32 v5, v1
	v_pk_add_f32 v[0:1], v[4:5], v[44:45]
	v_permlane32_swap_b32_e32 v62, v30
	v_cvt_pk_bf16_f32 v2, v0, v1
	v_pk_mul_f32 v[4:5], v[136:137], v[0:1]
	v_permlane32_swap_b32_e32 v46, v14
	ds_write2_b32 v173, v6, v2 offset0:96 offset1:164
	v_pk_fma_f32 v[6:7], v[132:133], v[0:1], v[4:5] op_sel:[0,0,1] op_sel_hi:[1,1,0] neg_lo:[0,0,1] neg_hi:[0,0,1]
	v_pk_fma_f32 v[0:1], v[132:133], v[0:1], v[4:5] op_sel:[0,0,1] op_sel_hi:[1,1,0]
	v_mov_b32_e32 v2, v62
	v_mov_b32_e32 v3, v46
	v_mov_b32_e32 v7, v1
	v_pk_add_f32 v[0:1], v[6:7], v[2:3]
	v_permlane32_swap_b32_e32 v63, v31
	v_pk_mul_f32 v[2:3], v[136:137], v[0:1]
	v_cvt_pk_bf16_f32 v6, v0, v1
	v_pk_fma_f32 v[4:5], v[132:133], v[0:1], v[2:3] op_sel:[0,0,1] op_sel_hi:[1,1,0] neg_lo:[0,0,1] neg_hi:[0,0,1]
	v_pk_fma_f32 v[0:1], v[132:133], v[0:1], v[2:3] op_sel:[0,0,1] op_sel_hi:[1,1,0]
	v_permlane32_swap_b32_e32 v47, v15
	v_mov_b32_e32 v46, v63
	v_mov_b32_e32 v5, v1
	v_pk_add_f32 v[0:1], v[4:5], v[46:47]
	v_mov_b32_e32 v3, v12
	v_cvt_pk_bf16_f32 v2, v0, v1
	v_pk_mul_f32 v[4:5], v[136:137], v[0:1]
	ds_write2_b32 v174, v6, v2 offset0:104 offset1:172
	v_pk_fma_f32 v[6:7], v[132:133], v[0:1], v[4:5] op_sel:[0,0,1] op_sel_hi:[1,1,0] neg_lo:[0,0,1] neg_hi:[0,0,1]
	v_pk_fma_f32 v[0:1], v[132:133], v[0:1], v[4:5] op_sel:[0,0,1] op_sel_hi:[1,1,0]
	v_mov_b32_e32 v2, v28
	v_mov_b32_e32 v7, v1
	v_pk_add_f32 v[0:1], v[6:7], v[2:3]
	v_mov_b32_e32 v12, v29
	v_pk_mul_f32 v[2:3], v[136:137], v[0:1]
	v_cvt_pk_bf16_f32 v6, v0, v1
	v_pk_fma_f32 v[4:5], v[132:133], v[0:1], v[2:3] op_sel:[0,0,1] op_sel_hi:[1,1,0] neg_lo:[0,0,1] neg_hi:[0,0,1]
	v_pk_fma_f32 v[0:1], v[132:133], v[0:1], v[2:3] op_sel:[0,0,1] op_sel_hi:[1,1,0]
	v_mov_b32_e32 v3, v14
	v_mov_b32_e32 v5, v1
	v_pk_add_f32 v[0:1], v[4:5], v[12:13]
	v_mov_b32_e32 v14, v31
	v_cvt_pk_bf16_f32 v2, v0, v1
	v_pk_mul_f32 v[4:5], v[136:137], v[0:1]
	ds_write2_b32 v176, v6, v2 offset0:112 offset1:180
	v_pk_fma_f32 v[6:7], v[132:133], v[0:1], v[4:5] op_sel:[0,0,1] op_sel_hi:[1,1,0] neg_lo:[0,0,1] neg_hi:[0,0,1]
	v_pk_fma_f32 v[0:1], v[132:133], v[0:1], v[4:5] op_sel:[0,0,1] op_sel_hi:[1,1,0]
	v_mov_b32_e32 v2, v30
	v_mov_b32_e32 v7, v1
	v_pk_add_f32 v[0:1], v[6:7], v[2:3]
	v_lshlrev_b32_e32 v104, 1, v130
	v_pk_mul_f32 v[2:3], v[136:137], v[0:1]
	v_cvt_pk_bf16_f32 v6, v0, v1
	v_pk_fma_f32 v[4:5], v[132:133], v[0:1], v[2:3] op_sel:[0,0,1] op_sel_hi:[1,1,0] neg_lo:[0,0,1] neg_hi:[0,0,1]
	v_pk_fma_f32 v[0:1], v[132:133], v[0:1], v[2:3] op_sel:[0,0,1] op_sel_hi:[1,1,0]
	v_mov_b32_e32 v129, v105
	v_mov_b32_e32 v5, v1
	v_pk_add_f32 v[0:1], v[4:5], v[14:15]
	s_nop 0
	v_cvt_pk_bf16_f32 v0, v0, v1
	ds_write2_b32 v175, v6, v0 offset0:120 offset1:188
	ds_read_b128 v[0:3], v171
	ds_read_b128 v[4:7], v171 offset:64
	s_waitcnt lgkmcnt(1)
	v_mfma_f32_16x16x32_bf16 v[0:3], v[80:83], v[0:3], 0
	s_waitcnt lgkmcnt(0)
	v_mfma_f32_16x16x32_bf16 v[0:3], v[76:79], v[4:7], v[0:3]
	ds_read_b128 v[4:7], v171 offset:128
	ds_read_b128 v[8:11], v171 offset:192
	s_waitcnt lgkmcnt(1)
	v_mfma_f32_16x16x32_bf16 v[0:3], v[72:75], v[4:7], v[0:3]
	v_lshlrev_b32_e32 v4, 16, v148
	v_and_b32_e32 v5, 0xffff0000, v148
	s_waitcnt lgkmcnt(0)
	v_mfma_f32_16x16x32_bf16 v[0:3], v[68:71], v[8:11], v[0:3]
	v_lshlrev_b32_e32 v8, 16, v149
	v_and_b32_e32 v9, 0xffff0000, v149
	s_nop 5
	v_pk_fma_f32 v[0:1], v[64:65], v[4:5], v[0:1]
	v_pk_fma_f32 v[12:13], v[66:67], v[8:9], v[2:3]
	v_mul_f32_e32 v4, 0x3d372713, v0
	v_mul_f32_e32 v4, v0, v4
	v_fma_f32 v4, v0, v4, v0
	v_mul_f32_e32 v4, 0xbfcc422a, v4
	v_mul_f32_e32 v4, 0x3fb8aa3b, v4
	v_exp_f32_e32 v6, v4
	v_mul_f32_e32 v4, 0x3d372713, v1
	v_mul_f32_e32 v4, v1, v4
	v_fma_f32 v4, v1, v4, v1
	v_mul_f32_e32 v4, 0xbfcc422a, v4
	v_mul_f32_e32 v4, 0x3fb8aa3b, v4
	v_exp_f32_e32 v7, v4
	v_mul_f32_e32 v2, 0x3d372713, v12
	v_add_f32_e32 v6, 1.0, v6
	v_mul_f32_e32 v2, v12, v2
	v_add_f32_e32 v7, 1.0, v7
	v_rcp_f32_e32 v6, v6
	v_rcp_f32_e32 v7, v7
	v_fma_f32 v2, v12, v2, v12
	v_mul_f32_e32 v2, 0xbfcc422a, v2
	v_mul_f32_e32 v2, 0x3fb8aa3b, v2
	v_exp_f32_e32 v2, v2
	v_pk_mul_f32 v[16:17], v[0:1], v[6:7]
	v_mul_f32_e32 v0, 0x3d372713, v13
	v_mul_f32_e32 v0, v13, v0
	v_lshl_add_u64 v[4:5], v[134:135], 1, s[60:61]
	v_fma_f32 v0, v13, v0, v13
	v_lshl_add_u64 v[14:15], v[4:5], 0, v[104:105]
	v_add_f32_e32 v4, 1.0, v2
	v_mul_f32_e32 v5, 0xbfcc422a, v0
	ds_read_b128 v[0:3], v171 offset:4352
	v_mul_f32_e32 v5, 0x3fb8aa3b, v5
	v_exp_f32_e32 v8, v5
	v_rcp_f32_e32 v18, v4
	ds_read_b128 v[4:7], v171 offset:4416
	s_waitcnt lgkmcnt(1)
	v_mfma_f32_16x16x32_bf16 v[0:3], v[80:83], v[0:3], 0
	v_add_f32_e32 v8, 1.0, v8
	v_rcp_f32_e32 v19, v8
	ds_read_b128 v[8:11], v171 offset:4480
	s_waitcnt lgkmcnt(1)
	v_mfma_f32_16x16x32_bf16 v[0:3], v[76:79], v[4:7], v[0:3]
	ds_read_b128 v[4:7], v171 offset:4544
	v_pk_mul_f32 v[12:13], v[12:13], v[18:19]
	v_cvt_pk_bf16_f32 v16, v16, v17
	s_waitcnt lgkmcnt(1)
	v_mfma_f32_16x16x32_bf16 v[0:3], v[72:75], v[8:11], v[0:3]
	v_lshlrev_b32_e32 v10, 16, v141
	v_and_b32_e32 v11, 0xffff0000, v141
	v_lshl_add_u64 v[8:9], v[14:15], 0, v[128:129]
	s_waitcnt lgkmcnt(0)
	v_mfma_f32_16x16x32_bf16 v[0:3], v[68:71], v[4:7], v[0:3]
	v_lshlrev_b32_e32 v4, 16, v140
	v_and_b32_e32 v5, 0xffff0000, v140
	v_cvt_pk_bf16_f32 v17, v12, v13
	s_nop 4
	v_pk_fma_f32 v[0:1], v[64:65], v[4:5], v[0:1]
	v_pk_fma_f32 v[2:3], v[66:67], v[10:11], v[2:3]
	v_mul_f32_e32 v4, 0x3d372713, v0
	v_mul_f32_e32 v4, v0, v4
	v_fma_f32 v4, v0, v4, v0
	v_mul_f32_e32 v4, 0xbfcc422a, v4
	v_mul_f32_e32 v4, 0x3fb8aa3b, v4
	v_exp_f32_e32 v6, v4
	v_mul_f32_e32 v4, 0x3d372713, v1
	v_mul_f32_e32 v10, 0x3d372713, v2
	v_mul_f32_e32 v11, 0x3d372713, v3
	v_mul_f32_e32 v4, v1, v4
	v_mul_f32_e32 v10, v2, v10
	v_mul_f32_e32 v11, v3, v11
	v_fma_f32 v4, v1, v4, v1
	v_fma_f32 v10, v2, v10, v2
	v_fma_f32 v11, v3, v11, v3
	v_mul_f32_e32 v4, 0xbfcc422a, v4
	v_mul_f32_e32 v10, 0xbfcc422a, v10
	v_mul_f32_e32 v11, 0xbfcc422a, v11
	v_mul_f32_e32 v4, 0x3fb8aa3b, v4
	v_mul_f32_e32 v10, 0x3fb8aa3b, v10
	v_mul_f32_e32 v11, 0x3fb8aa3b, v11
	v_exp_f32_e32 v7, v4
	v_exp_f32_e32 v10, v10
	v_exp_f32_e32 v11, v11
	v_add_f32_e32 v6, 1.0, v6
	v_add_f32_e32 v7, 1.0, v7
	v_add_f32_e32 v10, 1.0, v10
	v_add_f32_e32 v11, 1.0, v11
	v_rcp_f32_e32 v6, v6
	v_rcp_f32_e32 v7, v7
	v_rcp_f32_e32 v10, v10
	v_rcp_f32_e32 v11, v11
	v_add_co_u32_e32 v4, vcc, s69, v8
	v_pk_mul_f32 v[0:1], v[0:1], v[6:7]
	s_nop 0
	v_addc_co_u32_e32 v5, vcc, 0, v9, vcc
	v_pk_mul_f32 v[2:3], v[2:3], v[10:11]
	v_cvt_pk_bf16_f32 v0, v0, v1
	v_cvt_pk_bf16_f32 v1, v2, v3
	v_add_co_u32_e32 v2, vcc, 0x3f8000, v8
	global_store_dwordx2 v[4:5], v[16:17], off
	s_nop 0
	v_addc_co_u32_e32 v3, vcc, 0, v9, vcc
	v_cmp_lt_i32_e32 vcc, s70, v131
	s_or_b64 s[14:15], vcc, s[14:15]
	global_store_dwordx2 v[2:3], v[0:1], off
	s_andn2_b64 exec, exec, s[14:15]
	s_cbranch_execnz .LBB0_526

; #define PG8_STAGE(bufoff, gbase, voff) do { _Pragma("unroll") for (int _i = 0; _i < 2; ++_i) \
;         __builtin_amdgcn_global_load_lds((const unsigned*)((const char*)(gbase) + (voff)[_i]), (LAS unsigned*)(lds + (bufoff) + ldsw + _i * 8192), 16, 0, 0); } while (0)
; #define PG8_WAIT_V(n) asm volatile("s_waitcnt vmcnt(" #n ")" ::: "memory")
; #define PG8_BAR __builtin_amdgcn_s_barrier()
; template <class Epi>
; __device__ __forceinline__ void gemm_phase(LAS unsigned char* lds, const Gemm g, const StaticOrder& S, const Epi& E) {
;     ...
;     PG8_STAGE(PG8_SB(0, 0), cB, voffB); PG8_STAGE(PG8_SA(0, 0), cA, voffA); PG8_STAGE(PG8_SB(0, 1), cB + hstepB, voffB); PG8_STAGE(PG8_SA(0, 1), cA + hstepA, voffA);
;     if (wr == 1) PG8_BAR;
;     PG8_WAIT_V(4); PG8_BAR;
;     PG8_STAGE(PG8_SB(1, 0), cB + kstep, voffB); PG8_STAGE(PG8_SA(1, 0), cA + kstep, voffA); PG8_STAGE(PG8_SB(1, 1), cB + hstepB + kstep, voffB);
;     PG8_WAIT_V(6); PG8_BAR;
.LBB0_630:
	s_lshl_b32 s12, s12, 5
	s_and_b32 s19, s12, 0x60
	s_mov_b64 s[12:13], 0x80
	s_add_i32 m0, s39, 0x18000
	v_lshl_add_u64 v[6:7], v[6:7], 0, s[12:13]
	s_lshl_b32 s18, s9, 13
	s_lshl_b32 s22, s19, 7
	s_waitcnt vmcnt(2)
	s_barrier
	global_load_lds_dwordx4 v[6:7], off
	v_lshl_add_u64 v[4:5], v[4:5], 0, s[12:13]
	s_add_i32 m0, s39, 0x1a000
	s_add_i32 s63, s39, 0x8000
	s_add_i32 s68, s39, 0xa000
	global_load_lds_dwordx4 v[4:5], off
	v_lshl_add_u64 v[2:3], v[2:3], 0, s[12:13]
	s_mov_b32 m0, s63
	s_add_u32 s14, s42, 0x40080
	global_load_lds_dwordx4 v[2:3], off
	v_lshl_add_u64 v[0:1], v[0:1], 0, s[12:13]
	s_mov_b32 m0, s68
	s_addc_u32 s15, s43, 0
	global_load_lds_dwordx4 v[0:1], off
	s_add_i32 m0, s39, 0x1c000
	v_lshl_add_u64 v[0:1], s[14:15], 0, v[158:159]
	global_load_lds_dwordx4 v[0:1], off
	v_lshl_add_u64 v[0:1], s[14:15], 0, v[162:163]
	s_add_i32 m0, s39, 0x1e000
	s_waitcnt lgkmcnt(0)
	s_add_u32 s14, s10, 0x1000
	global_load_lds_dwordx4 v[0:1], off
	v_lshrrev_b32_e32 v1, 1, v8
	v_and_b32_e32 v1, 24, v1
	v_and_b32_e32 v0, 15, v8
	v_lshlrev_b32_e32 v2, 1, v1
	v_lshl_or_b32 v182, s9, 6, v0
	v_lshl_or_b32 v0, v0, 6, v2
	v_lshlrev_b32_e32 v2, 2, v8
	v_and_b32_e32 v2, 32, v2
	v_bitop3_b32 v3, v0, s18, v2 bitop3:0xde
	v_bitop3_b32 v183, v0, s22, v2 bitop3:0xde
	v_lshlrev_b32_e32 v0, 14, v9
	v_and_b32_e32 v0, 0xffff8000, v0
	v_or_b32_e32 v184, s19, v1
	v_lshl_add_u32 v0, v10, 11, v0
	v_and_b32_e32 v1, 1, v9
	v_lshl_or_b32 v0, v1, 6, v0
	v_lshl_add_u32 v164, v11, 1, v0
	v_lshlrev_b32_e32 v0, 14, v12
	v_and_b32_e32 v0, 0xffff8000, v0
	s_waitcnt vmcnt(6)
	v_lshl_add_u32 v0, v13, 11, v0
	v_and_b32_e32 v1, 1, v12
	s_addc_u32 s15, s11, 0
	v_lshl_or_b32 v0, v1, 6, v0
	s_add_i32 s69, 0, 0x10000
	s_add_i32 s70, 0, 0x14000
	s_sext_i32_i8 s71, s8
	v_mov_b32_e32 v165, v159
	v_lshl_add_u32 v166, v14, 1, v0
	v_mov_b32_e32 v167, v159
	v_mov_b64_e32 v[168:169], 0x400
	v_mov_b64_e32 v[170:171], 0x3ff
	v_add_u32_e32 v185, s69, v183
	v_add_u32_e32 v186, 0, v3
	v_add_u32_e32 v187, s70, v183
	s_mov_b64 s[18:19], 0x80000
	s_mov_b64 s[22:23], 0x90000
	s_mov_b64 s[24:25], 0xa0000
	s_mov_b64 s[26:27], 0xb0000
	s_barrier

; #define PG8_STAGE(bufoff, gbase, voff) do { _Pragma("unroll") for (int _i = 0; _i < 2; ++_i) \
;         __builtin_amdgcn_global_load_lds((const unsigned*)((const char*)(gbase) + (voff)[_i]), (LAS unsigned*)(lds + (bufoff) + ldsw + _i * 8192), 16, 0, 0); } while (0)
; #define PG8_WAIT_V(n) asm volatile("s_waitcnt vmcnt(" #n ")" ::: "memory")
; #define PG8_BAR __builtin_amdgcn_s_barrier()
; template <class Epi>
; __device__ __forceinline__ void gemm_phase(LAS unsigned char* lds, const Gemm g, const StaticOrder& S, const Epi& E) {
;     ...
;     const int tid = tid_, wid = __builtin_amdgcn_readfirstlane(tid >> 6), lane = tid & 63, wr = wid >> 2, wc = wid & 3, fr = lane & 15, fq = lane >> 4;
;     const int K = g.K, nt = K / BK;
;     unsigned voffA[2], voffB[2];
; #pragma unroll
;     for (int i = 0; i < 2; ++i) { int R, C; stage_rc(tid * 16 + i * 8192, R, C); const int Rb = Epi::PERM ? ((R & ~31) + perm32(R & 31)) : R;
;         const int Ra = Epi::ROWPERM ? ((R & ~63) + 4 * (R & 15) + ((R >> 4) & 3)) : R;
;         voffA[i] = (unsigned)(Ra * g.lda + C) * 2u; voffB[i] = (unsigned)(Rb * g.ldb + C) * 2u; }
;     const size_t kstep = (size_t)(BK * 2);
;     const size_t hstepA = (size_t)HALF * g.lda * 2, hstepB = (size_t)HALF * g.ldb * 2;
;     const size_t tstepA = 2 * hstepA, tstepB = 2 * hstepB;
;     const unsigned ldsw = (unsigned)wid * 1024u;
;     const int aoff = lds_byte(wr * 64 + fr, fq * 8), boff = lds_byte(wc * 32 + fr, fq * 8);
;     ...
;     PG8_STAGE(PG8_SB(0, 0), cB, voffB); PG8_STAGE(PG8_SA(0, 0), cA, voffA); PG8_STAGE(PG8_SB(0, 1), cB + hstepB, voffB); PG8_STAGE(PG8_SA(0, 1), cA + hstepA, voffA);
;     if (wr == 1) PG8_BAR;
;     PG8_WAIT_V(4); PG8_BAR;
;     PG8_STAGE(PG8_SB(1, 0), cB + kstep, voffB); PG8_STAGE(PG8_SA(1, 0), cA + kstep, voffA); PG8_STAGE(PG8_SB(1, 1), cB + hstepB + kstep, voffB);
;     PG8_WAIT_V(6); PG8_BAR;
.LBB0_753:
	s_lshl_b32 s11, s11, 5
	s_mov_b64 s[20:21], 0x80
	s_and_b32 s11, s11, 0x60
	s_add_i32 m0, s9, 0x18000
	v_lshl_add_u64 v[6:7], v[6:7], 0, s[20:21]
	s_lshl_b32 s24, s28, 13
	s_lshl_b32 s25, s11, 7
	s_waitcnt vmcnt(2)
	s_barrier
	global_load_lds_dwordx4 v[6:7], off
	v_lshl_add_u64 v[4:5], v[4:5], 0, s[20:21]
	s_add_i32 m0, s9, 0x1a000
	s_add_i32 s72, s9, 0x8000
	s_add_i32 s73, s9, 0xa000
	global_load_lds_dwordx4 v[4:5], off
	v_lshl_add_u64 v[0:1], v[0:1], 0, s[20:21]
	s_mov_b32 m0, s72
	s_add_u32 s12, s44, 0x40080
	global_load_lds_dwordx4 v[0:1], off
	v_lshl_add_u64 v[0:1], v[2:3], 0, s[20:21]
	s_mov_b32 m0, s73
	s_addc_u32 s13, s45, 0
	global_load_lds_dwordx4 v[0:1], off
	s_add_i32 m0, s9, 0x1c000
	v_lshl_add_u64 v[0:1], s[12:13], 0, v[214:215]
	global_load_lds_dwordx4 v[0:1], off
	v_lshl_add_u64 v[0:1], s[12:13], 0, v[210:211]
	s_add_i32 m0, s9, 0x1e000
	s_sext_i32_i16 s41, s10
	global_load_lds_dwordx4 v[0:1], off
	v_lshrrev_b32_e32 v1, 1, v10
	v_and_b32_e32 v0, 15, v10
	v_and_b32_e32 v1, 24, v1
	v_lshlrev_b32_e32 v2, 1, v1
	v_lshlrev_b32_e32 v3, 2, v0
	v_lshl_or_b32 v2, v0, 6, v2
	v_and_b32_e32 v4, 32, v3
	v_or_b32_e32 v218, s11, v1
	v_cmp_eq_u32_e64 s[10:11], 15, v0
	v_bitop3_b32 v5, v2, s24, v4 bitop3:0xde
	v_bitop3_b32 v235, v2, s25, v4 bitop3:0xde
	s_lshl_b32 s34, s28, 11
	s_and_b64 s[24:25], s[10:11], s[14:15]
	s_cmp_gt_i32 s28, 0
	v_cmp_eq_u32_e32 vcc, 0, v0
	s_cselect_b64 s[14:15], -1, 0
	s_and_b64 s[26:27], vcc, s[14:15]
	s_cmp_gt_i32 s28, -2
	v_or_b32_e32 v0, s28, v0
	s_cselect_b64 s[14:15], -1, 0
	v_cmp_eq_u32_e64 s[12:13], 0, v0
	v_lshl_or_b32 v236, s28, 6, v3
	s_and_b64 s[28:29], vcc, s[14:15]
	v_lshlrev_b32_e32 v0, 2, v218
	v_mov_b32_e32 v1, v215
	s_add_i32 s14, s34, 0
	v_lshl_add_u64 v[220:221], s[18:19], 0, v[0:1]
	v_lshl_add_u64 v[222:223], s[22:23], 0, v[0:1]
	s_add_i32 s15, s14, 0x20000
	s_add_i32 s14, s14, 0x1f800
	v_and_b32_e32 v1, 1, v14
	v_add_u32_e32 v237, s15, v0
	v_add_u32_e32 v238, s14, v0
	v_add3_u32 v0, v16, v17, v18
	v_lshlrev_b32_e32 v1, 6, v1
	v_lshl_or_b32 v0, v0, 11, v1
	s_mov_b64 s[30:31], 0x40080
	v_lshl_add_u32 v0, v15, 1, v0
	v_mov_b32_e32 v1, v215
	v_lshl_add_u64 v[224:225], v[0:1], 0, s[30:31]
	v_and_b32_e32 v1, 1, v8
	v_add3_u32 v0, v11, v12, v13
	v_lshlrev_b32_e32 v1, 6, v1
	s_waitcnt vmcnt(6)
	v_lshl_or_b32 v0, v0, 11, v1
	v_lshl_add_u32 v0, v9, 1, v0
	v_mov_b32_e32 v1, v215
	s_add_i32 s74, 0, 0x10000
	s_add_i32 s75, 0, 0x14000
	v_add_u32_e32 v239, 0xfffffe10, v237
	v_add_u32_e32 v240, 0xfffffa10, v237
	v_add_u32_e32 v241, 0xfffffc10, v237
	v_add_u32_e32 v242, 0xfffff810, v237
	v_lshl_add_u64 v[226:227], v[0:1], 0, s[30:31]
	v_mov_b64_e32 v[228:229], 0xb00
	v_mov_b64_e32 v[230:231], 0xaff
	v_add_u32_e32 v243, s74, v235
	v_add_u32_e32 v244, 0, v5
	v_add_u32_e32 v245, s75, v235
	s_movk_i32 s76, 0x1600
	s_barrier
	s_branch .LBB0_755

; #define PG8_STAGE(bufoff, gbase, voff) do { _Pragma("unroll") for (int _i = 0; _i < 2; ++_i) \
;         __builtin_amdgcn_global_load_lds((const unsigned*)((const char*)(gbase) + (voff)[_i]), (LAS unsigned*)(lds + (bufoff) + ldsw + _i * 8192), 16, 0, 0); } while (0)
; #define PG8_WAIT_V(n) asm volatile("s_waitcnt vmcnt(" #n ")" ::: "memory")
; #define PG8_BAR __builtin_amdgcn_s_barrier()
; template <class Epi>
; __device__ __forceinline__ void gemm_phase(LAS unsigned char* lds, const Gemm g, const StaticOrder& S, const Epi& E) {
;     ...
;     PG8_STAGE(PG8_SB(0, 0), cB, voffB); PG8_STAGE(PG8_SA(0, 0), cA, voffA); PG8_STAGE(PG8_SB(0, 1), cB + hstepB, voffB); PG8_STAGE(PG8_SA(0, 1), cA + hstepA, voffA);
;     if (wr == 1) PG8_BAR;
;     PG8_WAIT_V(4); PG8_BAR;
;     PG8_STAGE(PG8_SB(1, 0), cB + kstep, voffB); PG8_STAGE(PG8_SA(1, 0), cA + kstep, voffA); PG8_STAGE(PG8_SB(1, 1), cB + hstepB + kstep, voffB);
;     PG8_WAIT_V(6); PG8_BAR;
.LBB0_848:
	s_lshl_b32 s12, s12, 5
	s_mov_b64 s[20:21], 0x80
	s_and_b32 s15, s12, 0x60
	s_add_i32 m0, s8, 0x18000
	v_lshl_add_u64 v[6:7], v[6:7], 0, s[20:21]
	s_lshl_b32 s14, s10, 13
	s_lshl_b32 s22, s15, 7
	s_waitcnt vmcnt(2)
	s_barrier
	global_load_lds_dwordx4 v[6:7], off
	v_lshl_add_u64 v[4:5], v[4:5], 0, s[20:21]
	s_add_i32 m0, s8, 0x1a000
	s_add_i32 s41, s8, 0x8000
	s_add_i32 s42, s8, 0xa000
	global_load_lds_dwordx4 v[4:5], off
	v_lshl_add_u64 v[2:3], v[2:3], 0, s[20:21]
	s_mov_b32 m0, s41
	s_add_u32 s12, s30, 0xb0080
	global_load_lds_dwordx4 v[2:3], off
	v_lshl_add_u64 v[0:1], v[0:1], 0, s[20:21]
	s_mov_b32 m0, s42
	s_addc_u32 s13, s31, 0
	global_load_lds_dwordx4 v[0:1], off
	s_add_i32 m0, s8, 0x1c000
	v_lshl_add_u64 v[0:1], s[12:13], 0, v[128:129]
	global_load_lds_dwordx4 v[0:1], off
	v_lshl_add_u64 v[0:1], s[12:13], 0, v[130:131]
	s_add_i32 m0, s8, 0x1e000
	s_mov_b64 s[12:13], 0xb0080
	global_load_lds_dwordx4 v[0:1], off
	v_bfe_u32 v0, v8, 4, 2
	v_and_b32_e32 v1, 15, v8
	v_lshlrev_b32_e32 v2, 4, v0
	v_lshl_or_b32 v146, s10, 6, v1
	v_lshl_or_b32 v1, v1, 6, v2
	v_lshlrev_b32_e32 v2, 2, v8
	v_and_b32_e32 v2, 32, v2
	v_bitop3_b32 v3, v1, s14, v2 bitop3:0xde
	v_bitop3_b32 v147, v1, s22, v2 bitop3:0xde
	v_lshl_or_b32 v148, v0, 2, s15
	v_lshrrev_b32_e32 v1, 1, v9
	v_mul_lo_u32 v0, v11, s11
	s_mov_b32 s10, 0xb000
	v_mad_u64_u32 v[0:1], s[14:15], v1, s10, v[0:1]
	v_or_b32_e32 v0, v0, v10
	v_add_lshl_u32 v0, v0, v12, 1
	v_mov_b32_e32 v1, v129
	v_lshl_add_u64 v[132:133], v[0:1], 0, s[12:13]
	v_lshrrev_b32_e32 v1, 1, v13
	v_mul_lo_u32 v0, v14, s11
	v_mad_u64_u32 v[0:1], s[10:11], v1, s10, v[0:1]
	s_waitcnt vmcnt(6)
	v_or_b32_e32 v0, v0, v15
	v_add_lshl_u32 v0, v0, v16, 1
	v_mov_b32_e32 v1, v129
	s_add_i32 s43, 0, 0x10000
	s_add_i32 s44, 0, 0x14000
	v_lshl_add_u64 v[134:135], v[0:1], 0, s[12:13]
	v_mov_b64_e32 v[136:137], 0x200
	v_mov_b64_e32 v[138:139], 0x1ff
	v_add_u32_e32 v149, s43, v147
	v_add_u32_e32 v150, 0, v3
	v_add_u32_e32 v151, s44, v147
	s_mov_b64 s[22:23], 0x80000
	s_mov_b64 s[24:25], 0x90000
	s_mov_b64 s[26:27], 0xa0000
	s_barrier

; #define PG8_STAGE(bufoff, gbase, voff) do { _Pragma("unroll") for (int _i = 0; _i < 2; ++_i) \
;         __builtin_amdgcn_global_load_lds((const unsigned*)((const char*)(gbase) + (voff)[_i]), (LAS unsigned*)(lds + (bufoff) + ldsw + _i * 8192), 16, 0, 0); } while (0)
; #define PG8_WAIT_V(n) asm volatile("s_waitcnt vmcnt(" #n ")" ::: "memory")
; #define PG8_BAR __builtin_amdgcn_s_barrier()
; template <class Epi>
; __device__ __forceinline__ void gemm_phase(LAS unsigned char* lds, const Gemm g, const StaticOrder& S, const Epi& E) {
;     ...
;     const int tid = tid_, wid = __builtin_amdgcn_readfirstlane(tid >> 6), lane = tid & 63, wr = wid >> 2, wc = wid & 3, fr = lane & 15, fq = lane >> 4;
;     const int K = g.K, nt = K / BK;
;     unsigned voffA[2], voffB[2];
; #pragma unroll
;     for (int i = 0; i < 2; ++i) { int R, C; stage_rc(tid * 16 + i * 8192, R, C); const int Rb = Epi::PERM ? ((R & ~31) + perm32(R & 31)) : R;
;         const int Ra = Epi::ROWPERM ? ((R & ~63) + 4 * (R & 15) + ((R >> 4) & 3)) : R;
;         voffA[i] = (unsigned)(Ra * g.lda + C) * 2u; voffB[i] = (unsigned)(Rb * g.ldb + C) * 2u; }
;     const size_t kstep = (size_t)(BK * 2);
;     const size_t hstepA = (size_t)HALF * g.lda * 2, hstepB = (size_t)HALF * g.ldb * 2;
;     const size_t tstepA = 2 * hstepA, tstepB = 2 * hstepB;
;     const unsigned ldsw = (unsigned)wid * 1024u;
;     const int aoff = lds_byte(wr * 64 + fr, fq * 8), boff = lds_byte(wc * 32 + fr, fq * 8);
;     ...
;     PG8_STAGE(PG8_SB(0, 0), cB, voffB); PG8_STAGE(PG8_SA(0, 0), cA, voffA); PG8_STAGE(PG8_SB(0, 1), cB + hstepB, voffB); PG8_STAGE(PG8_SA(0, 1), cA + hstepA, voffA);
;     if (wr == 1) PG8_BAR;
;     PG8_WAIT_V(4); PG8_BAR;
;     PG8_STAGE(PG8_SB(1, 0), cB + kstep, voffB); PG8_STAGE(PG8_SA(1, 0), cA + kstep, voffA); PG8_STAGE(PG8_SB(1, 1), cB + hstepB + kstep, voffB);
;     PG8_WAIT_V(6); PG8_BAR;
.LBB0_981:
	s_lshl_b32 s4, s4, 5
	s_mov_b64 s[28:29], 0x80
	s_and_b32 s12, s4, 0x60
	s_add_i32 m0, s91, 0x18000
	v_lshl_add_u64 v[6:7], v[6:7], 0, s[28:29]
	s_lshl_b32 s7, s6, 13
	s_lshl_b32 s13, s12, 7
	s_waitcnt vmcnt(2)
	s_barrier
	global_load_lds_dwordx4 v[6:7], off
	v_lshl_add_u64 v[4:5], v[4:5], 0, s[28:29]
	s_add_i32 m0, s91, 0x1a000
	s_add_i32 s4, s91, 0x8000
	s_add_i32 s5, s91, 0xa000
	global_load_lds_dwordx4 v[4:5], off
	v_lshl_add_u64 v[2:3], v[2:3], 0, s[28:29]
	s_mov_b32 m0, s4
	s_add_u32 s10, s82, 0x40080
	global_load_lds_dwordx4 v[2:3], off
	v_lshl_add_u64 v[0:1], v[0:1], 0, s[28:29]
	s_mov_b32 m0, s5
	s_addc_u32 s11, s83, 0
	global_load_lds_dwordx4 v[0:1], off
	s_add_i32 m0, s91, 0x1c000
	v_lshl_add_u64 v[0:1], s[10:11], 0, v[164:165]
	global_load_lds_dwordx4 v[0:1], off
	v_lshl_add_u64 v[0:1], s[10:11], 0, v[168:169]
	s_add_i32 m0, s91, 0x1e000
	s_mul_i32 s38, s6, 0xc00
	global_load_lds_dwordx4 v[0:1], off
	v_lshrrev_b32_e32 v1, 1, v8
	v_and_b32_e32 v0, 15, v8
	v_and_b32_e32 v1, 24, v1
	v_lshlrev_b32_e32 v2, 1, v1
	v_lshlrev_b32_e32 v3, 2, v0
	v_lshl_or_b32 v2, v0, 6, v2
	v_and_b32_e32 v4, 32, v3
	v_bitop3_b32 v173, v2, s13, v4 bitop3:0xde
	v_or_b32_e32 v172, s12, v1
	v_cmp_eq_u32_e64 s[12:13], 15, v0
	s_and_b64 s[30:31], s[12:13], s[16:17]
	s_cmp_gt_i32 s6, 0
	v_cmp_eq_u32_e32 vcc, 0, v0
	s_cselect_b64 s[16:17], -1, 0
	s_and_b64 s[34:35], vcc, s[16:17]
	s_cmp_gt_i32 s6, -2
	v_bitop3_b32 v5, v2, s7, v4 bitop3:0xde
	v_lshl_or_b32 v204, s6, 6, v3
	v_or_b32_e32 v0, s6, v0
	s_cselect_b64 s[6:7], -1, 0
	s_and_b64 s[36:37], vcc, s[6:7]
	s_add_i32 s6, s38, 0
	s_add_i32 s7, s6, 0x20000
	s_waitcnt lgkmcnt(0)
	s_add_u32 s38, s20, 0x1000
	s_addc_u32 s39, s21, 0
	s_add_u32 s40, s20, 0x2000
	s_addc_u32 s41, s21, 0
	v_cmp_eq_u32_e64 s[14:15], 0, v0
	v_lshlrev_b32_e32 v0, 2, v172
	s_add_u32 s42, s20, 0x3000
	v_add_u32_e32 v205, s7, v0
	s_addc_u32 s43, s21, 0
	s_add_i32 s7, s6, 0x1f400
	s_add_i32 s6, s6, 0x1f600
	v_and_b32_e32 v1, 1, v9
	v_add_u32_e32 v206, s7, v0
	v_add_u32_e32 v210, s6, v0
	v_add3_u32 v0, v11, v12, v13
	v_lshlrev_b32_e32 v1, 6, v1
	v_lshl_or_b32 v0, v0, 11, v1
	v_and_b32_e32 v1, 1, v14
	v_lshl_add_u32 v170, v10, 1, v0
	v_add3_u32 v0, v16, v17, v18
	v_lshlrev_b32_e32 v1, 6, v1
	s_mov_b64 s[10:11], 0x40080
	s_waitcnt vmcnt(6)
	v_lshl_or_b32 v0, v0, 11, v1
	v_lshl_add_u64 v[174:175], v[170:171], 0, s[10:11]
	v_lshl_add_u32 v170, v15, 1, v0
	s_add_i32 s93, 0, 0x10000
	s_add_i32 s96, 0, 0x14000
	v_add_u32_e32 v207, 0xfffffc10, v205
	v_add_u32_e32 v208, 0xfffff810, v205
	v_add_u32_e32 v209, 0xfffff410, v205
	v_add_u32_e32 v211, 0xfffffe10, v205
	v_add_u32_e32 v212, 0xfffffa10, v205
	v_add_u32_e32 v213, 0xfffff610, v205
	v_lshl_add_u64 v[176:177], v[170:171], 0, s[10:11]
	v_mov_b64_e32 v[178:179], 0x400
	v_mov_b64_e32 v[180:181], 0x3ff
	v_add_u32_e32 v214, s93, v173
	v_add_u32_e32 v215, 0, v5
	v_add_u32_e32 v216, s96, v173
	s_mov_b32 s6, 0x40000
	s_mov_b64 s[44:45], 0x40800
	s_mov_b64 s[46:47], 0x41000
	s_mov_b32 s7, 0x41000
	s_mov_b64 s[48:49], 0x41800
	v_mov_b32_e32 v217, 0x200
	v_mov_b32_e32 v218, 0x210
	s_barrier
	s_branch .LBB0_983

; #define PG8_STAGE(bufoff, gbase, voff) do { _Pragma("unroll") for (int _i = 0; _i < 2; ++_i) \
;         __builtin_amdgcn_global_load_lds((const unsigned*)((const char*)(gbase) + (voff)[_i]), (LAS unsigned*)(lds + (bufoff) + ldsw + _i * 8192), 16, 0, 0); } while (0)
; #define PG8_WAIT_V(n) asm volatile("s_waitcnt vmcnt(" #n ")" ::: "memory")
; #define PG8_BAR __builtin_amdgcn_s_barrier()
; template <class Epi>
; __device__ __forceinline__ void gemm_phase(LAS unsigned char* lds, const Gemm g, const StaticOrder& S, const Epi& E) {
;     ...
;     PG8_STAGE(PG8_SB(0, 0), cB, voffB); PG8_STAGE(PG8_SA(0, 0), cA, voffA); PG8_STAGE(PG8_SB(0, 1), cB + hstepB, voffB); PG8_STAGE(PG8_SA(0, 1), cA + hstepA, voffA);
;     if (wr == 1) PG8_BAR;
;     PG8_WAIT_V(4); PG8_BAR;
;     PG8_STAGE(PG8_SB(1, 0), cB + kstep, voffB); PG8_STAGE(PG8_SA(1, 0), cA + kstep, voffA); PG8_STAGE(PG8_SB(1, 1), cB + hstepB + kstep, voffB);
;     PG8_WAIT_V(6); PG8_BAR;
.LBB0_1231:
	s_lshl_b32 s12, s12, 5
	s_and_b32 s17, s12, 0x60
	s_mov_b64 s[12:13], 0x80
	s_add_i32 m0, s8, 0x18000
	v_lshl_add_u64 v[6:7], v[6:7], 0, s[12:13]
	s_lshl_b32 s16, s11, 13
	s_lshl_b32 s22, s17, 7
	s_waitcnt vmcnt(2)
	s_barrier
	global_load_lds_dwordx4 v[6:7], off
	v_lshl_add_u64 v[4:5], v[4:5], 0, s[12:13]
	s_add_i32 m0, s8, 0x1a000
	s_add_i32 s46, s8, 0x8000
	s_add_i32 s47, s8, 0xa000
	global_load_lds_dwordx4 v[4:5], off
	v_lshl_add_u64 v[2:3], v[2:3], 0, s[12:13]
	s_mov_b32 m0, s46
	s_add_u32 s14, s40, 0x40080
	global_load_lds_dwordx4 v[2:3], off
	v_lshl_add_u64 v[0:1], v[0:1], 0, s[12:13]
	s_mov_b32 m0, s47
	s_addc_u32 s15, s41, 0
	global_load_lds_dwordx4 v[0:1], off
	s_add_i32 m0, s8, 0x1c000
	v_lshl_add_u64 v[0:1], s[14:15], 0, v[128:129]
	global_load_lds_dwordx4 v[0:1], off
	v_lshl_add_u64 v[0:1], s[14:15], 0, v[130:131]
	s_add_i32 m0, s8, 0x1e000
	s_add_i32 s48, 0, 0x10000
	global_load_lds_dwordx4 v[0:1], off
	v_bfe_u32 v0, v8, 4, 2
	v_and_b32_e32 v1, 15, v8
	v_lshlrev_b32_e32 v2, 4, v0
	v_lshl_or_b32 v146, s11, 6, v1
	v_lshl_or_b32 v1, v1, 6, v2
	v_lshlrev_b32_e32 v2, 2, v8
	v_lshl_or_b32 v148, v0, 2, s17
	v_lshlrev_b32_e32 v0, 14, v9
	v_and_b32_e32 v2, 32, v2
	v_and_b32_e32 v0, 0xffff8000, v0
	v_bitop3_b32 v3, v1, s16, v2 bitop3:0xde
	v_bitop3_b32 v147, v1, s22, v2 bitop3:0xde
	v_lshl_add_u32 v0, v10, 11, v0
	v_and_b32_e32 v1, 1, v9
	v_lshl_or_b32 v0, v1, 6, v0
	v_lshl_add_u32 v132, v11, 1, v0
	v_lshlrev_b32_e32 v0, 14, v12
	v_and_b32_e32 v0, 0xffff8000, v0
	s_waitcnt vmcnt(6)
	v_lshl_add_u32 v0, v13, 11, v0
	v_and_b32_e32 v1, 1, v12
	v_lshl_or_b32 v0, v1, 6, v0
	s_add_i32 s49, 0, 0x14000
	s_sext_i32_i8 s63, s10
	v_mov_b32_e32 v133, v129
	v_lshl_add_u32 v134, v14, 1, v0
	v_mov_b32_e32 v135, v129
	v_mov_b64_e32 v[136:137], 0x200
	v_mov_b64_e32 v[138:139], 0x1ff
	v_add_u32_e32 v149, s48, v147
	v_add_u32_e32 v150, 0, v3
	v_add_u32_e32 v151, s49, v147
	s_mov_b64 s[14:15], 0x80000
	s_mov_b64 s[16:17], 0x90000
	s_mov_b64 s[22:23], 0xa0000
	s_mov_b64 s[24:25], 0xb0000
	s_barrier

; #define LAS __attribute__((address_space(3)))
; template <class Epi>
; __device__ __forceinline__ void gemm_phase(LAS unsigned char* lds, const Gemm g, const StaticOrder& S, const Epi& E) {
;     ...
;     PG8_STAGE(PG8_SB(0, 0), cB, voffB); PG8_STAGE(PG8_SA(0, 0), cA, voffA); PG8_STAGE(PG8_SB(0, 1), cB + hstepB, voffB); PG8_STAGE(PG8_SA(0, 1), cA + hstepA, voffA);
;     if (wr == 1) PG8_BAR;
;     PG8_WAIT_V(4); PG8_BAR;
;     PG8_STAGE(PG8_SB(1, 0), cB + kstep, voffB); PG8_STAGE(PG8_SA(1, 0), cA + kstep, voffA); PG8_STAGE(PG8_SB(1, 1), cB + hstepB + kstep, voffB);
;     PG8_WAIT_V(6); PG8_BAR;
;     __device__ __forceinline__ void operator()(AccRef acc, const Unit& u, int wr, int wc, int fr, int fq) const {
;         const int clb = 32 * wc + 8 * fq;
;         f32x4 cwv[2][8];
;         { const float* cv = cw + 128 * u.pn + clb; const float* cg = cv + FH; const float* bp = cb + 128 * u.pn + clb;
;           cwv[0][0] = *(const f32x4*)(cv); cwv[0][1] = *(const f32x4*)(cv + F2); cwv[0][2] = *(const f32x4*)(cv + 2 * F2); cwv[0][3] = *(const f32x4*)(bp);
;           cwv[0][4] = *(const f32x4*)(cg); cwv[0][5] = *(const f32x4*)(cg + F2); cwv[0][6] = *(const f32x4*)(cg + 2 * F2); cwv[0][7] = *(const f32x4*)(bp + FH); }
;         if (fr == 15) {
; #pragma unroll
;             for (int ai = 0; ai < 2; ++ai)
; #pragma unroll
;                 for (int bj = 0; bj < 2; ++bj)
; #pragma unroll
;                     for (int n = 0; n < 2; ++n) { *(LAS f32x4*)(xch + ((ai * 2 + wr) * 2 + 0) * 256 + bj * 128 + clb + 4 * n) = acc[ai][bj][2][n]; *(LAS f32x4*)(xch + ((ai * 2 + wr) * 2 + 1) * 256 + bj * 128 + clb + 4 * n) = acc[ai][bj][3][n]; }
;         }
;         float* rawu = raw + (size_t)(u.pm * 22 + u.pn) * 1024;
;         if (wr == 0 && fr == 0) {
; #pragma unroll
;             for (int bj = 0; bj < 2; ++bj)
; #pragma unroll
;                 for (int n = 0; n < 2; ++n) { *(f32x4*)(rawu + 0 * 256 + bj * 128 + clb + 4 * n) = acc[0][bj][0][n]; *(f32x4*)(rawu + 1 * 256 + bj * 128 + clb + 4 * n) = acc[0][bj][1][n]; }
;         }
;         if (wr == 1 && fr == 15) {
; #pragma unroll
;             for (int bj = 0; bj < 2; ++bj)
; #pragma unroll
;                 for (int n = 0; n < 2; ++n) { *(f32x4*)(rawu + 2 * 256 + bj * 128 + clb + 4 * n) = acc[1][bj][2][n]; *(f32x4*)(rawu + 3 * 256 + bj * 128 + clb + 4 * n) = acc[1][bj][3][n]; }
;         }
.LBB0_1354:
	s_lshl_b32 s11, s11, 5
	s_mov_b64 s[24:25], 0x80
	s_and_b32 s11, s11, 0x60
	s_add_i32 m0, s9, 0x18000
	v_lshl_add_u64 v[6:7], v[6:7], 0, s[24:25]
	s_lshl_b32 s26, s30, 13
	s_lshl_b32 s27, s11, 7
	s_waitcnt vmcnt(2)
	s_barrier
	global_load_lds_dwordx4 v[6:7], off
	v_lshl_add_u64 v[4:5], v[4:5], 0, s[24:25]
	s_add_i32 m0, s9, 0x1a000
	s_add_i32 s78, s9, 0x8000
	s_add_i32 s79, s9, 0xa000
	global_load_lds_dwordx4 v[4:5], off
	v_lshl_add_u64 v[0:1], v[0:1], 0, s[24:25]
	s_mov_b32 m0, s78
	s_add_u32 s12, s46, 0x40080
	global_load_lds_dwordx4 v[0:1], off
	v_lshl_add_u64 v[0:1], v[2:3], 0, s[24:25]
	s_mov_b32 m0, s79
	s_addc_u32 s13, s47, 0
	global_load_lds_dwordx4 v[0:1], off
	s_add_i32 m0, s9, 0x1c000
	v_lshl_add_u64 v[0:1], s[12:13], 0, v[214:215]
	global_load_lds_dwordx4 v[0:1], off
	v_lshl_add_u64 v[0:1], s[12:13], 0, v[210:211]
	s_add_i32 m0, s9, 0x1e000
	s_sext_i32_i16 s43, s10
	global_load_lds_dwordx4 v[0:1], off
	v_lshrrev_b32_e32 v1, 1, v10
	v_and_b32_e32 v0, 15, v10
	v_and_b32_e32 v1, 24, v1
	v_lshlrev_b32_e32 v2, 1, v1
	v_lshlrev_b32_e32 v3, 2, v0
	v_lshl_or_b32 v2, v0, 6, v2
	v_and_b32_e32 v4, 32, v3
	v_or_b32_e32 v218, s11, v1
	v_cmp_eq_u32_e64 s[10:11], 15, v0
	v_bitop3_b32 v5, v2, s26, v4 bitop3:0xde
	v_bitop3_b32 v235, v2, s27, v4 bitop3:0xde
	s_lshl_b32 s36, s30, 11
	s_and_b64 s[26:27], s[10:11], s[14:15]
	s_cmp_gt_i32 s30, 0
	v_cmp_eq_u32_e32 vcc, 0, v0
	s_cselect_b64 s[14:15], -1, 0
	s_and_b64 s[28:29], vcc, s[14:15]
	s_cmp_gt_i32 s30, -2
	v_or_b32_e32 v0, s30, v0
	s_cselect_b64 s[14:15], -1, 0
	v_cmp_eq_u32_e64 s[12:13], 0, v0
	v_lshl_or_b32 v236, s30, 6, v3
	s_and_b64 s[30:31], vcc, s[14:15]
	v_lshlrev_b32_e32 v0, 2, v218
	v_mov_b32_e32 v1, v215
	s_add_i32 s14, s36, 0
	v_lshl_add_u64 v[220:221], s[16:17], 0, v[0:1]
	v_lshl_add_u64 v[222:223], s[22:23], 0, v[0:1]
	s_add_i32 s15, s14, 0x20000
	s_add_i32 s14, s14, 0x1f800
	v_and_b32_e32 v1, 1, v14
	v_add_u32_e32 v237, s15, v0
	v_add_u32_e32 v238, s14, v0
	v_add3_u32 v0, v16, v17, v18
	v_lshlrev_b32_e32 v1, 6, v1
	v_lshl_or_b32 v0, v0, 11, v1
	s_mov_b64 s[34:35], 0x40080
	v_lshl_add_u32 v0, v15, 1, v0
	v_mov_b32_e32 v1, v215
	v_lshl_add_u64 v[224:225], v[0:1], 0, s[34:35]
	v_and_b32_e32 v1, 1, v8
	v_add3_u32 v0, v11, v12, v13
	v_lshlrev_b32_e32 v1, 6, v1
	s_waitcnt vmcnt(6)
	v_lshl_or_b32 v0, v0, 11, v1
	v_lshl_add_u32 v0, v9, 1, v0
	v_mov_b32_e32 v1, v215
	s_add_i32 s80, 0, 0x10000
	s_add_i32 s81, 0, 0x14000
	v_add_u32_e32 v239, 0xfffffe10, v237
	v_add_u32_e32 v240, 0xfffffa10, v237
	v_add_u32_e32 v241, 0xfffffc10, v237
	v_add_u32_e32 v242, 0xfffff810, v237
	v_lshl_add_u64 v[226:227], v[0:1], 0, s[34:35]
	v_mov_b64_e32 v[228:229], 0xb00
	v_mov_b64_e32 v[230:231], 0xaff
	v_add_u32_e32 v243, s80, v235
	v_add_u32_e32 v244, 0, v5
	v_add_u32_e32 v245, s81, v235
	s_movk_i32 s82, 0x1600
	s_barrier
	s_branch .LBB0_1356

; #define PG8_STAGE(bufoff, gbase, voff) do { _Pragma("unroll") for (int _i = 0; _i < 2; ++_i) \
;         __builtin_amdgcn_global_load_lds((const unsigned*)((const char*)(gbase) + (voff)[_i]), (LAS unsigned*)(lds + (bufoff) + ldsw + _i * 8192), 16, 0, 0); } while (0)
; #define PG8_WAIT_V(n) asm volatile("s_waitcnt vmcnt(" #n ")" ::: "memory")
; #define PG8_BAR __builtin_amdgcn_s_barrier()
; template <class Epi>
; __device__ __forceinline__ void gemm_phase(LAS unsigned char* lds, const Gemm g, const StaticOrder& S, const Epi& E) {
;     ...
;     for (int i = 0; i < 2; ++i) { int R, C; stage_rc(tid * 16 + i * 8192, R, C); const int Rb = Epi::PERM ? ((R & ~31) + perm32(R & 31)) : R;
;         const int Ra = Epi::ROWPERM ? ((R & ~63) + 4 * (R & 15) + ((R >> 4) & 3)) : R;
;         voffA[i] = (unsigned)(Ra * g.lda + C) * 2u; voffB[i] = (unsigned)(Rb * g.ldb + C) * 2u; }
;     const size_t kstep = (size_t)(BK * 2);
;     const size_t hstepA = (size_t)HALF * g.lda * 2, hstepB = (size_t)HALF * g.ldb * 2;
;     const size_t tstepA = 2 * hstepA, tstepB = 2 * hstepB;
;     const unsigned ldsw = (unsigned)wid * 1024u;
;     const int aoff = lds_byte(wr * 64 + fr, fq * 8), boff = lds_byte(wc * 32 + fr, fq * 8);
;     ...
;     PG8_STAGE(PG8_SB(0, 0), cB, voffB); PG8_STAGE(PG8_SA(0, 0), cA, voffA); PG8_STAGE(PG8_SB(0, 1), cB + hstepB, voffB); PG8_STAGE(PG8_SA(0, 1), cA + hstepA, voffA);
;     if (wr == 1) PG8_BAR;
;     PG8_WAIT_V(4); PG8_BAR;
;     PG8_STAGE(PG8_SB(1, 0), cB + kstep, voffB); PG8_STAGE(PG8_SA(1, 0), cA + kstep, voffA); PG8_STAGE(PG8_SB(1, 1), cB + hstepB + kstep, voffB);
;     PG8_WAIT_V(6); PG8_BAR;
.LBB0_1449:
	s_lshl_b32 s12, s12, 5
	s_mov_b64 s[22:23], 0x80
	s_and_b32 s15, s12, 0x60
	s_add_i32 m0, s8, 0x18000
	v_lshl_add_u64 v[6:7], v[6:7], 0, s[22:23]
	s_lshl_b32 s14, s10, 13
	s_lshl_b32 s24, s15, 7
	s_waitcnt vmcnt(2)
	s_barrier
	global_load_lds_dwordx4 v[6:7], off
	v_lshl_add_u64 v[4:5], v[4:5], 0, s[22:23]
	s_add_i32 m0, s8, 0x1a000
	s_add_i32 s43, s8, 0x8000
	s_add_i32 s44, s8, 0xa000
	global_load_lds_dwordx4 v[4:5], off
	v_lshl_add_u64 v[2:3], v[2:3], 0, s[22:23]
	s_mov_b32 m0, s43
	s_add_u32 s12, s34, 0xb0080
	global_load_lds_dwordx4 v[2:3], off
	v_lshl_add_u64 v[0:1], v[0:1], 0, s[22:23]
	s_mov_b32 m0, s44
	s_addc_u32 s13, s35, 0
	global_load_lds_dwordx4 v[0:1], off
	s_add_i32 m0, s8, 0x1c000
	v_lshl_add_u64 v[0:1], s[12:13], 0, v[128:129]
	global_load_lds_dwordx4 v[0:1], off
	v_lshl_add_u64 v[0:1], s[12:13], 0, v[130:131]
	s_add_i32 m0, s8, 0x1e000
	s_mov_b64 s[12:13], 0xb0080
	global_load_lds_dwordx4 v[0:1], off
	v_bfe_u32 v0, v8, 4, 2
	v_and_b32_e32 v1, 15, v8
	v_lshlrev_b32_e32 v2, 4, v0
	v_lshl_or_b32 v146, s10, 6, v1
	v_lshl_or_b32 v1, v1, 6, v2
	v_lshlrev_b32_e32 v2, 2, v8
	v_and_b32_e32 v2, 32, v2
	v_bitop3_b32 v3, v1, s14, v2 bitop3:0xde
	v_bitop3_b32 v147, v1, s24, v2 bitop3:0xde
	v_lshl_or_b32 v148, v0, 2, s15
	v_lshrrev_b32_e32 v1, 1, v9
	v_mul_lo_u32 v0, v11, s11
	s_mov_b32 s10, 0xb000
	v_mad_u64_u32 v[0:1], s[14:15], v1, s10, v[0:1]
	v_or_b32_e32 v0, v0, v10
	v_add_lshl_u32 v0, v0, v12, 1
	v_mov_b32_e32 v1, v129
	v_lshl_add_u64 v[132:133], v[0:1], 0, s[12:13]
	v_lshrrev_b32_e32 v1, 1, v13
	v_mul_lo_u32 v0, v14, s11
	v_mad_u64_u32 v[0:1], s[10:11], v1, s10, v[0:1]
	s_waitcnt vmcnt(6)
	v_or_b32_e32 v0, v0, v15
	v_add_lshl_u32 v0, v0, v16, 1
	v_mov_b32_e32 v1, v129
	s_add_i32 s45, 0, 0x10000
	s_add_i32 s46, 0, 0x14000
	v_lshl_add_u64 v[134:135], v[0:1], 0, s[12:13]
	v_mov_b64_e32 v[136:137], 0x200
	v_mov_b64_e32 v[138:139], 0x1ff
	v_add_u32_e32 v149, s45, v147
	v_add_u32_e32 v150, 0, v3
	v_add_u32_e32 v151, s46, v147
	s_mov_b64 s[24:25], 0x80000
	s_mov_b64 s[26:27], 0x90000
	s_mov_b64 s[28:29], 0xa0000
	s_barrier

; #define PG8_WAIT_V(n) asm volatile("s_waitcnt vmcnt(" #n ")" ::: "memory")
; #define PG8_BAR __builtin_amdgcn_s_barrier()
; template <class Epi>
; __device__ __forceinline__ void gemm_phase(LAS unsigned char* lds, const Gemm g, const StaticOrder& S, const Epi& E) {
;     ...
;     PG8_STAGE(PG8_SB(0, 0), cB, voffB); PG8_STAGE(PG8_SA(0, 0), cA, voffA); PG8_STAGE(PG8_SB(0, 1), cB + hstepB, voffB); PG8_STAGE(PG8_SA(0, 1), cA + hstepA, voffA);
;     if (wr == 1) PG8_BAR;
;     PG8_WAIT_V(4); PG8_BAR;
;     PG8_STAGE(PG8_SB(1, 0), cB + kstep, voffB); PG8_STAGE(PG8_SA(1, 0), cA + kstep, voffA); PG8_STAGE(PG8_SB(1, 1), cB + hstepB + kstep, voffB);
;     PG8_WAIT_V(6); PG8_BAR;
;     __device__ __forceinline__ void operator()(AccRef acc, const Unit& u, int wr, int wc, int fr, int fq) const {
;         const int which = u.pn >> 2, row0 = u.pm * 256 + wr * 64 + fr, col0 = (u.pn & 3) * 256 + wc * 64 + 8 * fq;
;         bf16_t* dst = QKV + (size_t)which * ((size_t)T * D);
;         f32x4 gv[2][2];
; #pragma unroll
;         for (int bj = 0; bj < 2; ++bj)
; #pragma unroll
;             for (int n = 0; n < 2; ++n) { const f32x4 a = *(const f32x4*)(qg + 32 * bj + 8 * fq + 4 * n), b = *(const f32x4*)(kg + 32 * bj + 8 * fq + 4 * n);
;                 gv[bj][n] = which == 0 ? a : (which == 1 ? b : (f32x4){1.f, 1.f, 1.f, 1.f}); }
; #pragma unroll
;         for (int ai = 0; ai < 2; ++ai)
; #pragma unroll
;             for (int m = 0; m < 4; ++m) {
;                 float sc = 1.0f;
;                 if (which < 2) { float ss = 0.f;
; #pragma unroll
;                     for (int bj = 0; bj < 2; ++bj)
; #pragma unroll
;                         for (int n = 0; n < 2; ++n) { const f32x4 v = acc[ai][bj][m][n]; ss += (v[0] * v[0] + v[1] * v[1]) + (v[2] * v[2] + v[3] * v[3]); }
;                     ss += __shfl_xor(ss, 16); ss += __shfl_xor(ss, 32);
;                     sc = rsqrtf(ss * (1.0f / 64.0f) + 1e-6f) * (which == 0 ? 0.18033688011112042f : 1.0f); }
;                 const int row = row0 + ai * 128 + m * 16;
;                 bf16_t* rp = dst + (size_t)row * D + col0;
;                 bf16_t* kp = dst + ((size_t)((row >> 11) * 16 + (u.pn & 3) * 4 + wc) * 64 * SEQ) + (size_t)((((row & 2047) >> 5) * 4 + (fq >> 1)) * 64 + (row & 31) + 32 * (fq & 1)) * 8;
.LBB0_1578:
	s_mov_b64 s[16:17], 0x80
	s_and_b32 s43, s10, 3
	s_add_i32 m0, s8, 0x18000
	v_lshl_add_u64 v[6:7], v[6:7], 0, s[16:17]
	s_lshl_b32 s44, s11, 6
	s_lshl_b32 s22, s11, 13
	s_lshl_b32 s23, s43, 12
	s_waitcnt vmcnt(2)
	s_barrier
	global_load_lds_dwordx4 v[6:7], off
	v_lshl_add_u64 v[4:5], v[4:5], 0, s[16:17]
	s_add_i32 m0, s8, 0x1a000
	s_add_i32 s45, s8, 0x8000
	s_add_i32 s46, s8, 0xa000
	global_load_lds_dwordx4 v[4:5], off
	v_lshl_add_u64 v[2:3], v[2:3], 0, s[16:17]
	s_mov_b32 m0, s45
	s_add_u32 s10, s36, 0x40080
	global_load_lds_dwordx4 v[2:3], off
	v_lshl_add_u64 v[0:1], v[0:1], 0, s[16:17]
	s_mov_b32 m0, s46
	s_addc_u32 s11, s37, 0
	global_load_lds_dwordx4 v[0:1], off
	s_add_i32 m0, s8, 0x1c000
	v_lshl_add_u64 v[0:1], s[10:11], 0, v[146:147]
	global_load_lds_dwordx4 v[0:1], off
	v_lshl_add_u64 v[0:1], s[10:11], 0, v[150:151]
	s_add_i32 m0, s8, 0x1e000
	v_and_b32_e32 v174, 15, v8
	global_load_lds_dwordx4 v[0:1], off
	v_lshrrev_b32_e32 v0, 4, v8
	v_bfe_u32 v176, v0, 1, 1
	v_lshlrev_b32_e32 v0, 14, v9
	v_bfe_u32 v1, v8, 4, 2
	v_and_b32_e32 v0, 0xffff8000, v0
	v_lshlrev_b32_e32 v2, 3, v1
	v_lshlrev_b32_e32 v3, 4, v1
	v_lshlrev_b32_e32 v152, 5, v1
	v_lshl_add_u32 v0, v10, 11, v0
	v_and_b32_e32 v1, 1, v9
	v_lshl_or_b32 v0, v1, 6, v0
	v_lshl_add_u32 v158, v11, 1, v0
	v_lshlrev_b32_e32 v0, 14, v12
	v_lshlrev_b32_e32 v4, 2, v8
	v_and_b32_e32 v0, 0xffff8000, v0
	v_lshl_or_b32 v3, v174, 6, v3
	v_and_b32_e32 v4, 32, v4
	s_waitcnt vmcnt(6)
	v_lshl_add_u32 v0, v13, 11, v0
	v_and_b32_e32 v1, 1, v12
	v_bitop3_b32 v5, v3, s22, v4 bitop3:0xde
	v_bitop3_b32 v175, v3, s23, v4 bitop3:0xde
	v_and_or_b32 v177, v152, 32, v174
	v_lshl_or_b32 v0, v1, 6, v0
	s_add_i32 s48, 0, 0x10000
	s_add_i32 s49, 0, 0x14000
	v_or_b32_e32 v178, 16, v177
	s_waitcnt lgkmcnt(0)
	v_lshl_add_u64 v[154:155], s[14:15], 0, v[152:153]
	v_lshl_add_u64 v[156:157], s[12:13], 0, v[152:153]
	v_lshl_or_b32 v179, s43, 6, v2
	v_mov_b32_e32 v159, v153
	v_lshl_add_u32 v160, v14, 1, v0
	v_mov_b32_e32 v161, v153
	v_mov_b64_e32 v[162:163], 0x600
	v_mov_b64_e32 v[164:165], 0x5ff
	s_movk_i32 s47, 0xc1
	v_add_u32_e32 v180, s48, v175
	v_add_u32_e32 v181, 0, v5
	v_add_u32_e32 v182, s49, v175
	v_mov_b32_e32 v183, 0x358637bd
	s_mov_b32 s63, 0x800000
	s_movk_i32 s72, 0xf8
	s_movk_i32 s73, 0xfc
	v_mbcnt_hi_u32_b32 v184, -1, v234
	s_barrier
	s_branch .LBB0_1580

; #define PG8_STAGE(bufoff, gbase, voff) do { _Pragma("unroll") for (int _i = 0; _i < 2; ++_i) \
;         __builtin_amdgcn_global_load_lds((const unsigned*)((const char*)(gbase) + (voff)[_i]), (LAS unsigned*)(lds + (bufoff) + ldsw + _i * 8192), 16, 0, 0); } while (0)
; #define PG8_WAIT_V(n) asm volatile("s_waitcnt vmcnt(" #n ")" ::: "memory")
; #define PG8_BAR __builtin_amdgcn_s_barrier()
; template <class Epi>
; __device__ __forceinline__ void gemm_phase(LAS unsigned char* lds, const Gemm g, const StaticOrder& S, const Epi& E) {
;     ...
;     for (int i = 0; i < 2; ++i) { int R, C; stage_rc(tid * 16 + i * 8192, R, C); const int Rb = Epi::PERM ? ((R & ~31) + perm32(R & 31)) : R;
;         const int Ra = Epi::ROWPERM ? ((R & ~63) + 4 * (R & 15) + ((R >> 4) & 3)) : R;
;         voffA[i] = (unsigned)(Ra * g.lda + C) * 2u; voffB[i] = (unsigned)(Rb * g.ldb + C) * 2u; }
;     const size_t kstep = (size_t)(BK * 2);
;     const size_t hstepA = (size_t)HALF * g.lda * 2, hstepB = (size_t)HALF * g.ldb * 2;
;     const size_t tstepA = 2 * hstepA, tstepB = 2 * hstepB;
;     const unsigned ldsw = (unsigned)wid * 1024u;
;     const int aoff = lds_byte(wr * 64 + fr, fq * 8), boff = lds_byte(wc * 32 + fr, fq * 8);
;     ...
;     PG8_STAGE(PG8_SB(0, 0), cB, voffB); PG8_STAGE(PG8_SA(0, 0), cA, voffA); PG8_STAGE(PG8_SB(0, 1), cB + hstepB, voffB); PG8_STAGE(PG8_SA(0, 1), cA + hstepA, voffA);
;     if (wr == 1) PG8_BAR;
;     PG8_WAIT_V(4); PG8_BAR;
;     PG8_STAGE(PG8_SB(1, 0), cB + kstep, voffB); PG8_STAGE(PG8_SA(1, 0), cA + kstep, voffA); PG8_STAGE(PG8_SB(1, 1), cB + hstepB + kstep, voffB);
;     PG8_WAIT_V(6); PG8_BAR;
.LBB0_1812:
	s_lshl_b32 s12, s12, 5
	s_and_b32 s17, s12, 0x60
	s_mov_b64 s[12:13], 0x80
	s_add_i32 m0, s8, 0x18000
	v_lshl_add_u64 v[6:7], v[6:7], 0, s[12:13]
	s_lshl_b32 s16, s11, 13
	s_lshl_b32 s18, s17, 7
	s_waitcnt vmcnt(2)
	s_barrier
	global_load_lds_dwordx4 v[6:7], off
	v_lshl_add_u64 v[4:5], v[4:5], 0, s[12:13]
	s_add_i32 m0, s8, 0x1a000
	s_add_i32 s42, s8, 0x8000
	s_add_i32 s43, s8, 0xa000
	global_load_lds_dwordx4 v[4:5], off
	v_lshl_add_u64 v[2:3], v[2:3], 0, s[12:13]
	s_mov_b32 m0, s42
	s_add_u32 s14, s36, 0x40080
	global_load_lds_dwordx4 v[2:3], off
	v_lshl_add_u64 v[0:1], v[0:1], 0, s[12:13]
	s_mov_b32 m0, s43
	s_addc_u32 s15, s37, 0
	global_load_lds_dwordx4 v[0:1], off
	s_add_i32 m0, s8, 0x1c000
	v_lshl_add_u64 v[0:1], s[14:15], 0, v[128:129]
	global_load_lds_dwordx4 v[0:1], off
	v_lshl_add_u64 v[0:1], s[14:15], 0, v[130:131]
	s_add_i32 m0, s8, 0x1e000
	s_add_i32 s44, 0, 0x10000
	global_load_lds_dwordx4 v[0:1], off
	v_bfe_u32 v0, v8, 4, 2
	v_and_b32_e32 v1, 15, v8
	v_lshlrev_b32_e32 v2, 4, v0
	v_lshl_or_b32 v146, s11, 6, v1
	v_lshl_or_b32 v1, v1, 6, v2
	v_lshlrev_b32_e32 v2, 2, v8
	v_lshl_or_b32 v148, v0, 2, s17
	v_lshlrev_b32_e32 v0, 14, v9
	v_and_b32_e32 v2, 32, v2
	v_and_b32_e32 v0, 0xffff8000, v0
	v_bitop3_b32 v3, v1, s16, v2 bitop3:0xde
	v_bitop3_b32 v147, v1, s18, v2 bitop3:0xde
	v_lshl_add_u32 v0, v10, 11, v0
	v_and_b32_e32 v1, 1, v9
	v_lshl_or_b32 v0, v1, 6, v0
	v_lshl_add_u32 v132, v11, 1, v0
	v_lshlrev_b32_e32 v0, 14, v12
	v_and_b32_e32 v0, 0xffff8000, v0
	s_waitcnt vmcnt(6)
	v_lshl_add_u32 v0, v13, 11, v0
	v_and_b32_e32 v1, 1, v12
	v_lshl_or_b32 v0, v1, 6, v0
	s_add_i32 s45, 0, 0x14000
	s_sext_i32_i8 s46, s10
	v_mov_b32_e32 v133, v129
	v_lshl_add_u32 v134, v14, 1, v0
	v_mov_b32_e32 v135, v129
	v_mov_b64_e32 v[136:137], 0x200
	v_mov_b64_e32 v[138:139], 0x1ff
	v_add_u32_e32 v149, s44, v147
	v_add_u32_e32 v150, 0, v3
	v_add_u32_e32 v151, s45, v147
	s_mov_b64 s[14:15], 0x80000
	s_mov_b64 s[16:17], 0x90000
	s_mov_b64 s[18:19], 0xa0000
	s_mov_b64 s[20:21], 0xb0000
	s_barrier

; #define LAS __attribute__((address_space(3)))
; template <class Epi>
; __device__ __forceinline__ void gemm_phase(LAS unsigned char* lds, const Gemm g, const StaticOrder& S, const Epi& E) {
;     ...
;     PG8_STAGE(PG8_SB(0, 0), cB, voffB); PG8_STAGE(PG8_SA(0, 0), cA, voffA); PG8_STAGE(PG8_SB(0, 1), cB + hstepB, voffB); PG8_STAGE(PG8_SA(0, 1), cA + hstepA, voffA);
;     if (wr == 1) PG8_BAR;
;     PG8_WAIT_V(4); PG8_BAR;
;     PG8_STAGE(PG8_SB(1, 0), cB + kstep, voffB); PG8_STAGE(PG8_SA(1, 0), cA + kstep, voffA); PG8_STAGE(PG8_SB(1, 1), cB + hstepB + kstep, voffB);
;     PG8_WAIT_V(6); PG8_BAR;
;     __device__ __forceinline__ void operator()(AccRef acc, const Unit& u, int wr, int wc, int fr, int fq) const {
;         const int clb = 32 * wc + 8 * fq;
;         f32x4 cwv[2][8];
;         { const float* cv = cw + 128 * u.pn + clb; const float* cg = cv + FH; const float* bp = cb + 128 * u.pn + clb;
;           cwv[0][0] = *(const f32x4*)(cv); cwv[0][1] = *(const f32x4*)(cv + F2); cwv[0][2] = *(const f32x4*)(cv + 2 * F2); cwv[0][3] = *(const f32x4*)(bp);
;           cwv[0][4] = *(const f32x4*)(cg); cwv[0][5] = *(const f32x4*)(cg + F2); cwv[0][6] = *(const f32x4*)(cg + 2 * F2); cwv[0][7] = *(const f32x4*)(bp + FH); }
;         if (fr == 15) {
; #pragma unroll
;             for (int ai = 0; ai < 2; ++ai)
; #pragma unroll
;                 for (int bj = 0; bj < 2; ++bj)
; #pragma unroll
;                     for (int n = 0; n < 2; ++n) { *(LAS f32x4*)(xch + ((ai * 2 + wr) * 2 + 0) * 256 + bj * 128 + clb + 4 * n) = acc[ai][bj][2][n]; *(LAS f32x4*)(xch + ((ai * 2 + wr) * 2 + 1) * 256 + bj * 128 + clb + 4 * n) = acc[ai][bj][3][n]; }
;         }
;         float* rawu = raw + (size_t)(u.pm * 22 + u.pn) * 1024;
;         if (wr == 0 && fr == 0) {
; #pragma unroll
;             for (int bj = 0; bj < 2; ++bj)
; #pragma unroll
;                 for (int n = 0; n < 2; ++n) { *(f32x4*)(rawu + 0 * 256 + bj * 128 + clb + 4 * n) = acc[0][bj][0][n]; *(f32x4*)(rawu + 1 * 256 + bj * 128 + clb + 4 * n) = acc[0][bj][1][n]; }
;         }
;         if (wr == 1 && fr == 15) {
; #pragma unroll
;             for (int bj = 0; bj < 2; ++bj)
; #pragma unroll
;                 for (int n = 0; n < 2; ++n) { *(f32x4*)(rawu + 2 * 256 + bj * 128 + clb + 4 * n) = acc[1][bj][2][n]; *(f32x4*)(rawu + 3 * 256 + bj * 128 + clb + 4 * n) = acc[1][bj][3][n]; }
;         }
.LBB0_1935:
	s_lshl_b32 s1, s1, 5
	s_mov_b64 s[16:17], 0x80
	s_and_b32 s1, s1, 0x60
	s_add_i32 m0, s45, 0x18000
	v_lshl_add_u64 v[6:7], v[6:7], 0, s[16:17]
	s_lshl_b32 s18, s22, 13
	s_lshl_b32 s19, s1, 7
	s_waitcnt vmcnt(2)
	s_barrier
	global_load_lds_dwordx4 v[6:7], off
	v_lshl_add_u64 v[4:5], v[4:5], 0, s[16:17]
	s_add_i32 m0, s45, 0x1a000
	s_add_i32 s57, s45, 0x8000
	s_add_i32 s58, s45, 0xa000
	global_load_lds_dwordx4 v[4:5], off
	v_lshl_add_u64 v[0:1], v[0:1], 0, s[16:17]
	s_mov_b32 m0, s57
	s_add_u32 s8, s38, 0x40080
	global_load_lds_dwordx4 v[0:1], off
	v_lshl_add_u64 v[0:1], v[2:3], 0, s[16:17]
	s_mov_b32 m0, s58
	s_addc_u32 s9, s39, 0
	global_load_lds_dwordx4 v[0:1], off
	s_add_i32 m0, s45, 0x1c000
	v_lshl_add_u64 v[0:1], s[8:9], 0, v[214:215]
	global_load_lds_dwordx4 v[0:1], off
	v_lshl_add_u64 v[0:1], s[8:9], 0, v[210:211]
	s_add_i32 m0, s45, 0x1e000
	s_sext_i32_i16 s35, s0
	global_load_lds_dwordx4 v[0:1], off
	v_lshrrev_b32_e32 v1, 1, v10
	v_and_b32_e32 v0, 15, v10
	v_and_b32_e32 v1, 24, v1
	v_lshlrev_b32_e32 v2, 1, v1
	v_lshlrev_b32_e32 v3, 2, v0
	v_lshl_or_b32 v2, v0, 6, v2
	v_and_b32_e32 v4, 32, v3
	v_or_b32_e32 v218, s1, v1
	v_cmp_eq_u32_e64 s[0:1], 15, v0
	v_bitop3_b32 v5, v2, s18, v4 bitop3:0xde
	v_bitop3_b32 v234, v2, s19, v4 bitop3:0xde
	s_lshl_b32 s26, s22, 11
	s_and_b64 s[18:19], s[0:1], s[10:11]
	s_cmp_gt_i32 s22, 0
	v_cmp_eq_u32_e32 vcc, 0, v0
	s_cselect_b64 s[10:11], -1, 0
	s_and_b64 s[20:21], vcc, s[10:11]
	s_cmp_gt_i32 s22, -2
	v_or_b32_e32 v0, s22, v0
	s_cselect_b64 s[10:11], -1, 0
	v_cmp_eq_u32_e64 s[8:9], 0, v0
	v_lshl_or_b32 v235, s22, 6, v3
	s_and_b64 s[22:23], vcc, s[10:11]
	v_lshlrev_b32_e32 v0, 2, v218
	v_mov_b32_e32 v1, v215
	s_add_i32 s10, s26, 0
	v_lshl_add_u64 v[220:221], s[12:13], 0, v[0:1]
	v_lshl_add_u64 v[222:223], s[14:15], 0, v[0:1]
	s_add_i32 s11, s10, 0x20000
	s_add_i32 s10, s10, 0x1f800
	v_and_b32_e32 v1, 1, v14
	v_add_u32_e32 v236, s11, v0
	v_add_u32_e32 v237, s10, v0
	v_add3_u32 v0, v16, v17, v18
	v_lshlrev_b32_e32 v1, 6, v1
	v_lshl_or_b32 v0, v0, 11, v1
	s_mov_b64 s[24:25], 0x40080
	v_lshl_add_u32 v0, v15, 1, v0
	v_mov_b32_e32 v1, v215
	v_lshl_add_u64 v[224:225], v[0:1], 0, s[24:25]
	v_and_b32_e32 v1, 1, v8
	v_add3_u32 v0, v11, v12, v13
	v_lshlrev_b32_e32 v1, 6, v1
	s_waitcnt vmcnt(6)
	v_lshl_or_b32 v0, v0, 11, v1
	v_lshl_add_u32 v0, v9, 1, v0
	v_mov_b32_e32 v1, v215
	s_add_i32 s59, 0, 0x10000
	s_add_i32 s62, 0, 0x14000
	v_add_u32_e32 v238, 0xfffffe10, v236
	v_add_u32_e32 v239, 0xfffffa10, v236
	v_add_u32_e32 v240, 0xfffffc10, v236
	v_add_u32_e32 v241, 0xfffff810, v236
	v_lshl_add_u64 v[226:227], v[0:1], 0, s[24:25]
	v_mov_b64_e32 v[228:229], 0xb00
	v_mov_b64_e32 v[230:231], 0xaff
	v_add_u32_e32 v242, s59, v234
	v_add_u32_e32 v243, 0, v5
	v_add_u32_e32 v244, s62, v234
	s_movk_i32 s63, 0x1600
	s_barrier
	s_branch .LBB0_1937

; #define PG8_STAGE(bufoff, gbase, voff) do { _Pragma("unroll") for (int _i = 0; _i < 2; ++_i) \
;         __builtin_amdgcn_global_load_lds((const unsigned*)((const char*)(gbase) + (voff)[_i]), (LAS unsigned*)(lds + (bufoff) + ldsw + _i * 8192), 16, 0, 0); } while (0)
; #define PG8_WAIT_V(n) asm volatile("s_waitcnt vmcnt(" #n ")" ::: "memory")
; #define PG8_BAR __builtin_amdgcn_s_barrier()
; template <class Epi>
; __device__ __forceinline__ void gemm_phase(LAS unsigned char* lds, const Gemm g, const StaticOrder& S, const Epi& E) {
;     ...
;     for (int i = 0; i < 2; ++i) { int R, C; stage_rc(tid * 16 + i * 8192, R, C); const int Rb = Epi::PERM ? ((R & ~31) + perm32(R & 31)) : R;
;         const int Ra = Epi::ROWPERM ? ((R & ~63) + 4 * (R & 15) + ((R >> 4) & 3)) : R;
;         voffA[i] = (unsigned)(Ra * g.lda + C) * 2u; voffB[i] = (unsigned)(Rb * g.ldb + C) * 2u; }
;     const size_t kstep = (size_t)(BK * 2);
;     const size_t hstepA = (size_t)HALF * g.lda * 2, hstepB = (size_t)HALF * g.ldb * 2;
;     const size_t tstepA = 2 * hstepA, tstepB = 2 * hstepB;
;     const unsigned ldsw = (unsigned)wid * 1024u;
;     const int aoff = lds_byte(wr * 64 + fr, fq * 8), boff = lds_byte(wc * 32 + fr, fq * 8);
;     ...
;     PG8_STAGE(PG8_SB(0, 0), cB, voffB); PG8_STAGE(PG8_SA(0, 0), cA, voffA); PG8_STAGE(PG8_SB(0, 1), cB + hstepB, voffB); PG8_STAGE(PG8_SA(0, 1), cA + hstepA, voffA);
;     if (wr == 1) PG8_BAR;
;     PG8_WAIT_V(4); PG8_BAR;
;     PG8_STAGE(PG8_SB(1, 0), cB + kstep, voffB); PG8_STAGE(PG8_SA(1, 0), cA + kstep, voffA); PG8_STAGE(PG8_SB(1, 1), cB + hstepB + kstep, voffB);
;     PG8_WAIT_V(6); PG8_BAR;
.LBB0_2030:
	s_lshl_b32 s4, s4, 5
	s_mov_b64 s[10:11], 0x80
	s_and_b32 s7, s4, 0x60
	s_add_i32 m0, s30, 0x18000
	v_lshl_add_u64 v[6:7], v[6:7], 0, s[10:11]
	s_lshl_b32 s6, s0, 13
	s_lshl_b32 s12, s7, 7
	s_waitcnt vmcnt(2)
	s_barrier
	global_load_lds_dwordx4 v[6:7], off
	v_lshl_add_u64 v[4:5], v[4:5], 0, s[10:11]
	s_add_i32 m0, s30, 0x1a000
	s_add_i32 s36, s30, 0x8000
	s_add_i32 s37, s30, 0xa000
	global_load_lds_dwordx4 v[4:5], off
	v_lshl_add_u64 v[2:3], v[2:3], 0, s[10:11]
	s_mov_b32 m0, s36
	s_add_u32 s4, s20, 0xb0080
	global_load_lds_dwordx4 v[2:3], off
	v_lshl_add_u64 v[0:1], v[0:1], 0, s[10:11]
	s_mov_b32 m0, s37
	s_addc_u32 s5, s21, 0
	global_load_lds_dwordx4 v[0:1], off
	s_add_i32 m0, s30, 0x1c000
	v_lshl_add_u64 v[0:1], s[4:5], 0, v[128:129]
	global_load_lds_dwordx4 v[0:1], off
	v_lshl_add_u64 v[0:1], s[4:5], 0, v[130:131]
	s_add_i32 m0, s30, 0x1e000
	s_mov_b64 s[4:5], 0xb0080
	global_load_lds_dwordx4 v[0:1], off
	v_bfe_u32 v0, v219, 4, 2
	v_and_b32_e32 v1, 15, v219
	v_lshlrev_b32_e32 v2, 4, v0
	v_lshl_or_b32 v146, s0, 6, v1
	v_lshl_or_b32 v1, v1, 6, v2
	v_lshlrev_b32_e32 v2, 2, v219
	v_and_b32_e32 v2, 32, v2
	v_bitop3_b32 v3, v1, s6, v2 bitop3:0xde
	v_bitop3_b32 v147, v1, s12, v2 bitop3:0xde
	v_lshl_or_b32 v148, v0, 2, s7
	v_lshrrev_b32_e32 v1, 1, v8
	v_mul_lo_u32 v0, v10, s1
	s_mov_b32 s0, 0xb000
	v_mad_u64_u32 v[0:1], s[6:7], v1, s0, v[0:1]
	v_or_b32_e32 v0, v0, v9
	v_add_lshl_u32 v0, v0, v11, 1
	v_mov_b32_e32 v1, v129
	v_lshl_add_u64 v[132:133], v[0:1], 0, s[4:5]
	v_lshrrev_b32_e32 v1, 1, v12
	v_mul_lo_u32 v0, v13, s1
	v_mad_u64_u32 v[0:1], s[0:1], v1, s0, v[0:1]
	s_waitcnt vmcnt(6)
	v_or_b32_e32 v0, v0, v14
	v_add_lshl_u32 v0, v0, v15, 1
	v_mov_b32_e32 v1, v129
	s_add_i32 s38, 0, 0x10000
	s_add_i32 s39, 0, 0x14000
	v_lshl_add_u64 v[134:135], v[0:1], 0, s[4:5]
	v_mov_b64_e32 v[136:137], 0x200
	v_mov_b64_e32 v[138:139], 0x1ff
	v_add_u32_e32 v149, s38, v147
	v_add_u32_e32 v150, 0, v3
	v_add_u32_e32 v151, s39, v147
	s_mov_b64 s[12:13], 0x80000
	s_mov_b64 s[14:15], 0x90000
	s_mov_b64 s[16:17], 0xa0000
	s_barrier
